# attention V-fragment LDS reads: every ds_read2_b64 (half-rate, 32-bank, 2-way conflicts at the 144-B row stride) replaced by two ds_read_b64, lgkmcnt waits recomputed
# speedup vs baseline: 1.0254x; 1.0083x over previous
.LBB0_1113:
	s_mov_b64 s[18:19], -1
	s_and_b64 vcc, exec, s[16:17]
	s_cbranch_vccz .LBB0_1103
	s_lshl_b32 s16, s20, 4
	s_and_b32 s18, s16, 0x70
	s_bfe_u32 s19, s20, 0x40003
	s_and_b32 s21, s20, 0x7f
	s_load_dwordx2 s[16:17], s[14:15], 0x88
	s_or_b32 s22, s18, s19
	s_and_b64 s[18:19], s[82:83], exec
	v_readlane_b32 s18, v254, 63
	v_readlane_b32 s19, v255, 0
	s_cselect_b32 s62, s22, s21
	s_lshl_b64 s[18:19], s[18:19], 2
	s_waitcnt lgkmcnt(0)
	s_add_u32 s16, s16, s18
	s_addc_u32 s17, s17, s19
	s_cmpk_gt_u32 s20, 0x7f
	s_mov_b64 s[18:19], -1
	s_cbranch_scc0 .LBB0_1169
	s_ashr_i32 s63, s20, 7
	s_mov_b64 s[22:23], -1
	s_mov_b64 s[18:19], 0
	s_cmp_lt_i32 s63, 2
	s_mov_b64 s[20:21], 0
	s_cbranch_scc1 .LBB0_1129
	s_cmp_eq_u32 s63, 2
	s_mov_b64 s[20:21], -1
	s_cbranch_scc0 .LBB0_1137
	s_lshr_b32 s20, s62, 3
	s_lshl_b32 s22, s62, 7
	s_lshl_b32 s21, s20, 8
	s_and_b32 s22, s22, 0x80
	s_or_b32 s26, s21, s22
	s_lshl_b32 s21, s26, 10
	s_add_u32 s22, s37, s21
	s_addc_u32 s23, s38, 0
	s_lshl_b32 s21, s62, 6
	s_and_b32 s27, s21, 0x180
	v_mov_b32_e32 v158, v244
	s_or_b32 s66, s27, 64
	s_lshl_b32 s21, s20, 18
	s_add_u32 s24, s39, s21
	v_add_u32_e32 v14, 0x200, v158
	v_ashrrev_i32_e32 v0, 31, v158
	v_ashrrev_i32_e32 v2, 31, v14
	s_addc_u32 s25, s40, 0
	s_lshl_b32 s20, s27, 1
	v_lshrrev_b32_e32 v0, 28, v0
	v_lshrrev_b32_e32 v2, 28, v2
	s_add_u32 s24, s24, s20
	v_add_u32_e32 v0, v158, v0
	v_add_u32_e32 v2, v14, v2
	s_addc_u32 s25, s25, 0
	v_ashrrev_i32_e32 v146, 4, v0
	v_and_b32_e32 v0, -16, v0
	v_ashrrev_i32_e32 v148, 4, v2
	v_and_b32_e32 v2, -16, v2
	s_add_u32 s21, s41, s21
	v_sub_u32_e32 v22, v158, v0
	v_sub_u32_e32 v23, v14, v2
	s_addc_u32 s65, s44, 0
	s_lshl_b32 s64, s27, 9
	v_ashrrev_i32_e32 v147, 31, v146
	v_lshlrev_b32_e32 v168, 3, v22
	v_ashrrev_i32_e32 v149, 31, v148
	v_lshlrev_b32_e32 v170, 3, v23
	s_add_u32 s64, s21, s64
	v_readfirstlane_b32 s70, v158
	v_lshlrev_b64 v[150:151], 10, v[146:147]
	v_ashrrev_i32_e32 v169, 31, v168
	v_lshlrev_b64 v[154:155], 10, v[148:149]
	v_ashrrev_i32_e32 v171, 31, v170
	s_addc_u32 s65, s65, 0
	v_lshl_add_u64 v[0:1], s[24:25], 0, v[150:151]
	v_lshlrev_b64 v[152:153], 1, v[168:169]
	v_lshl_add_u64 v[2:3], s[24:25], 0, v[154:155]
	v_lshlrev_b64 v[156:157], 1, v[170:171]
	v_lshlrev_b32_e32 v8, 4, v158
	v_ashrrev_i32_e32 v16, 3, v158
	v_ashrrev_i32_e32 v18, 3, v14
	s_lshl_b32 s21, s70, 8
	v_and_b32_e32 v36, 31, v158
	v_lshl_add_u64 v[0:1], v[0:1], 0, v[152:153]
	v_lshl_add_u64 v[4:5], v[2:3], 0, v[156:157]
	v_and_b32_e32 v166, 0x70, v8
	v_mov_b32_e32 v167, v129
	v_ashrrev_i32_e32 v17, 31, v16
	v_ashrrev_i32_e32 v19, 31, v18
	s_and_b32 s21, s21, 0xc000
	global_load_dwordx4 v[0:3], v[0:1], off
	s_nop 0
	global_load_dwordx4 v[4:7], v[4:5], off
	v_lshl_add_u64 v[12:13], s[64:65], 0, v[166:167]
	v_lshlrev_b64 v[8:9], 9, v[16:17]
	v_lshlrev_b64 v[14:15], 9, v[18:19]
	v_lshl_or_b32 v17, v36, 9, s21
	v_lshl_add_u64 v[172:173], v[12:13], 0, v[8:9]
	v_lshl_add_u64 v[174:175], v[12:13], 0, v[14:15]
	v_lshlrev_b32_e32 v128, 1, v17
	s_cmpk_lt_u32 s70, 0x100
	global_load_dwordx4 v[8:11], v[172:173], off
	global_load_dwordx4 v[12:15], v[174:175], off
	v_lshl_add_u64 v[20:21], s[22:23], 0, v[128:129]
	s_cselect_b64 s[22:23], -1, 0
	s_and_b64 s[64:65], s[22:23], exec
	s_cselect_b32 s27, s27, s66
	v_bfe_u32 v37, v158, 5, 1
	s_lshl_b32 s68, s27, 1
	v_lshlrev_b32_e32 v162, 4, v37
	v_lshl_add_u64 v[20:21], v[20:21], 0, s[68:69]
	v_mov_b32_e32 v163, v129
	v_lshl_add_u64 v[20:21], v[20:21], 0, v[162:163]
	global_load_dwordx4 v[130:133], v[20:21], off
	global_load_dwordx4 v[134:137], v[20:21], off offset:32
	global_load_dwordx4 v[138:141], v[20:21], off offset:64
	global_load_dwordx4 v[142:145], v[20:21], off offset:96
	s_movk_i32 s65, 0x110
	v_mul_lo_u32 v165, v146, s65
	v_lshlrev_b32_e32 v167, 4, v22
	v_add3_u32 v38, 0, v165, v167
	v_mul_lo_u32 v176, v148, s65
	s_movk_i32 s65, 0x90
	s_ashr_i32 s64, s70, 8
	v_mul_lo_u32 v178, v16, s65
	v_mul_lo_u32 v179, v18, s65
	v_mul_u32_u24_e32 v17, 0x110, v36
	s_lshl_b32 s27, s64, 7
	v_lshlrev_b32_e32 v177, 4, v23
	v_add3_u32 v39, 0, v176, v177
	s_add_u32 s70, s24, 0x10000
	s_addc_u32 s71, s25, 0
	v_and_b32_e32 v43, 64, v248
	v_xor_b32_e32 v42, 32, v248
	v_add_u32_e32 v43, 64, v43
	v_cmp_lt_i32_e32 vcc, v42, v43
	v_lshlrev_b32_e32 v164, 3, v37
	s_waitcnt vmcnt(7)
	ds_write_b128 v38, v[0:3]
	v_add_u32_e32 v0, 0, v166
	v_add_u32_e32 v40, v0, v178
	v_add_u32_e32 v41, v0, v179
	v_add_u32_e32 v0, 0, v162
	v_add3_u32 v180, v0, v17, s27
	s_waitcnt vmcnt(6)
	ds_write_b128 v39, v[4:7]
	v_cndmask_b32_e32 v42, v248, v42, vcc
	v_lshlrev_b32_e32 v163, 2, v42
	s_waitcnt vmcnt(5)
	ds_write_b128 v40, v[8:11] offset:17408
	s_waitcnt vmcnt(4)
	ds_write_b128 v41, v[12:15] offset:17408
	s_waitcnt lgkmcnt(0)
	s_barrier
	ds_read_b128 v[0:3], v180
	ds_read_b128 v[16:19], v180 offset:32
	s_waitcnt vmcnt(3) lgkmcnt(1)
	v_mfma_f32_32x32x16_bf16 v[0:15], v[0:3], v[130:133], 0
	ds_read_b128 v[20:23], v180 offset:8704
	ds_read_b128 v[24:27], v180 offset:8736
	s_waitcnt vmcnt(2) lgkmcnt(2)
	v_mfma_f32_32x32x16_bf16 v[0:15], v[16:19], v[134:137], v[0:15]
	s_waitcnt lgkmcnt(1)
	v_mfma_f32_32x32x16_bf16 v[112:127], v[20:23], v[130:133], 0
	ds_read_b128 v[16:19], v180 offset:64
	ds_read_b128 v[20:23], v180 offset:96
	s_waitcnt vmcnt(1) lgkmcnt(1)
	v_mfma_f32_32x32x16_bf16 v[0:15], v[16:19], v[138:141], v[0:15]
	ds_read_b128 v[16:19], v180 offset:8768
	v_mfma_f32_32x32x16_bf16 v[112:127], v[24:27], v[134:137], v[112:127]
	ds_read_b128 v[24:27], v180 offset:8800
	s_waitcnt lgkmcnt(1)
	v_mfma_f32_32x32x16_bf16 v[112:127], v[16:19], v[138:141], v[112:127]
	v_lshl_add_u64 v[16:17], s[70:71], 0, v[150:151]
	v_lshl_add_u64 v[18:19], s[70:71], 0, v[154:155]
	v_lshl_add_u64 v[16:17], v[16:17], 0, v[152:153]
	v_lshl_add_u64 v[28:29], v[18:19], 0, v[156:157]
	global_load_dwordx4 v[16:19], v[16:17], off
	s_nop 0
	global_load_dwordx4 v[28:31], v[28:29], off
	s_add_u32 s70, s24, 0x20000
	s_addc_u32 s71, s25, 0
	s_waitcnt vmcnt(2)
	v_mfma_f32_32x32x16_bf16 v[0:15], v[20:23], v[142:145], v[0:15]
	global_load_dwordx4 v[20:23], v[172:173], off offset:128
	global_load_dwordx4 v[32:35], v[174:175], off offset:128
	s_waitcnt lgkmcnt(0)
	v_mfma_f32_32x32x16_bf16 v[112:127], v[24:27], v[142:145], v[112:127]
	s_nop 15
	s_nop 7
	s_waitcnt vmcnt(3)
	ds_write_b128 v38, v[16:19] offset:36864
	s_waitcnt vmcnt(2)
	ds_write_b128 v39, v[28:31] offset:36864
	s_waitcnt vmcnt(1)
	ds_write_b128 v40, v[20:23] offset:54272
	s_waitcnt vmcnt(0)
	ds_write_b128 v41, v[32:35] offset:54272
	v_max3_f32 v24, v0, v1, v112
	s_waitcnt lgkmcnt(0)
	v_max3_f32 v24, v24, v113, v2
	s_barrier
	v_max3_f32 v24, v24, v114, v114
	s_nop 0
	v_max3_f32 v24, v24, v3, v115
	ds_read_b128 v[16:19], v180 offset:36864
	ds_read_b128 v[20:23], v180 offset:36896
	v_max3_f32 v24, v24, v4, v116
	s_nop 0
	v_max3_f32 v24, v24, v5, v117
	s_nop 0
	v_max3_f32 v24, v24, v6, v118
	s_nop 0
	v_max3_f32 v24, v24, v7, v119
	s_nop 0
	v_max3_f32 v24, v24, v8, v120
	s_nop 0
	v_max3_f32 v24, v24, v9, v121
	s_nop 0
	v_max3_f32 v24, v24, v10, v122
	s_nop 0
	v_max3_f32 v24, v24, v11, v123
	s_nop 0
	v_max3_f32 v24, v24, v12, v124
	s_nop 0
	v_max3_f32 v24, v24, v13, v125
	s_nop 0
	v_max3_f32 v24, v24, v14, v126
	s_nop 0
	v_max3_f32 v24, v24, v15, v127
	ds_bpermute_b32 v25, v163, v24
	v_max_f32_e32 v24, v24, v24
	s_waitcnt lgkmcnt(0)
	v_max_f32_e32 v25, v25, v25
	v_max_f32_e32 v159, v24, v25
	v_add_f32_e32 v181, 0, v159
	v_xor_b32_e32 v64, 0x80000000, v181
	v_mov_b32_e32 v65, v64
	v_mov_b32_e32 v66, v64
	v_mov_b32_e32 v67, v64
	v_mov_b32_e32 v68, v64
	v_mov_b32_e32 v69, v64
	v_mov_b32_e32 v70, v64
	v_mov_b32_e32 v71, v64
	v_mov_b32_e32 v72, v64
	v_mov_b32_e32 v73, v64
	v_mov_b32_e32 v74, v64
	v_mov_b32_e32 v75, v64
	v_mov_b32_e32 v76, v64
	v_mov_b32_e32 v77, v64
	v_mov_b32_e32 v78, v64
	v_mov_b32_e32 v79, v64
	v_mov_b64_e32 v[110:111], v[78:79]
	v_mov_b64_e32 v[108:109], v[76:77]
	v_mfma_f32_32x32x16_bf16 v[80:95], v[16:19], v[130:133], v[64:79]
	ds_read_b128 v[16:19], v180 offset:45568
	v_mov_b64_e32 v[106:107], v[74:75]
	v_mov_b64_e32 v[104:105], v[72:73]
	v_mov_b64_e32 v[102:103], v[70:71]
	v_mov_b64_e32 v[100:101], v[68:69]
	v_mov_b64_e32 v[98:99], v[66:67]
	v_mov_b64_e32 v[96:97], v[64:65]
	ds_read_b128 v[24:27], v180 offset:45600
	v_mfma_f32_32x32x16_bf16 v[80:95], v[20:23], v[134:137], v[80:95]
	v_sub_f32_e32 v28, v3, v159
	v_sub_f32_e32 v4, v4, v159
	v_sub_f32_e32 v5, v5, v159
	v_sub_f32_e32 v6, v6, v159
	v_exp_f32_e32 v202, v4
	v_exp_f32_e32 v203, v5
	v_exp_f32_e32 v65, v6
	s_waitcnt lgkmcnt(1)
	v_mfma_f32_32x32x16_bf16 v[96:111], v[16:19], v[130:133], v[96:111]
	ds_read_b128 v[16:19], v180 offset:36928
	v_exp_f32_e32 v201, v28
	v_sub_f32_e32 v66, v8, v159
	v_sub_f32_e32 v67, v9, v159
	v_sub_f32_e32 v68, v10, v159
	v_sub_f32_e32 v69, v11, v159
	v_exp_f32_e32 v190, v66
	s_waitcnt lgkmcnt(1)
	v_mfma_f32_32x32x16_bf16 v[96:111], v[24:27], v[134:137], v[96:111]
	ds_read_b128 v[20:23], v180 offset:45632
	ds_read_b128 v[24:27], v180 offset:36960
	v_exp_f32_e32 v191, v67
	v_exp_f32_e32 v192, v68
	v_exp_f32_e32 v193, v69
	v_sub_f32_e32 v12, v12, v159
	v_sub_f32_e32 v13, v13, v159
	v_sub_f32_e32 v70, v14, v159
	s_waitcnt lgkmcnt(2)
	v_mfma_f32_32x32x16_bf16 v[80:95], v[16:19], v[138:141], v[80:95]
	v_mul_u32_u24_e32 v16, 0x90, v36
	v_add3_u32 v188, 0, v16, v164
	v_sub_f32_e32 v17, v0, v159
	v_sub_f32_e32 v18, v1, v159
	v_sub_f32_e32 v19, v2, v159
	ds_read_b128 v[0:3], v180 offset:45664
	v_add_u32_e32 v185, 0x4000, v188
	s_waitcnt lgkmcnt(2)
	v_mfma_f32_32x32x16_bf16 v[96:111], v[20:23], v[138:141], v[96:111]
	v_sub_f32_e32 v20, v7, v159
	ds_read_b64 v[4:5], v185 offset:1024
	ds_read_b64 v[6:7], v185 offset:1040
	v_add_u32_e32 v187, 0x5000, v188
	v_exp_f32_e32 v198, v17
	v_exp_f32_e32 v199, v18
	v_exp_f32_e32 v200, v19
	ds_read_b64 v[16:17], v187 offset:1536
	ds_read_b64 v[18:19], v187 offset:1552
	v_exp_f32_e32 v79, v20
	s_waitcnt lgkmcnt(4)
	v_mfma_f32_32x32x16_bf16 v[96:111], v[0:3], v[142:145], v[96:111]
	v_cvt_pk_bf16_f32 v0, v198, v199
	v_cvt_pk_bf16_f32 v1, v200, v201
	v_cvt_pk_bf16_f32 v2, v202, v203
	v_cvt_pk_bf16_f32 v3, v65, v79
	v_add_u32_e32 v184, 0x6800, v188
	ds_read_b64 v[66:67], v185 offset:1056
	ds_read_b64 v[68:69], v185 offset:1072
	v_add_u32_e32 v186, 0x7800, v188
	s_waitcnt lgkmcnt(4)
	v_mfma_f32_32x32x16_bf16 v[48:63], v[4:7], v[0:3], 0
	ds_read_b64 v[4:5], v184 offset:0
	ds_read_b64 v[6:7], v184 offset:16
	ds_read_b64 v[74:75], v187 offset:1568
	ds_read_b64 v[76:77], v187 offset:1584
	ds_read_b64 v[8:9], v186 offset:512
	ds_read_b64 v[10:11], v186 offset:528
	v_sub_f32_e32 v71, v15, v159
	v_exp_f32_e32 v194, v12
	v_exp_f32_e32 v195, v13
	v_exp_f32_e32 v196, v70
	s_waitcnt lgkmcnt(8)
	v_mfma_f32_32x32x16_bf16 v[32:47], v[16:19], v[0:3], 0
	v_exp_f32_e32 v197, v71
	v_cvt_pk_bf16_f32 v70, v190, v191
	v_cvt_pk_bf16_f32 v71, v192, v193
	v_cvt_pk_bf16_f32 v72, v194, v195
	v_cvt_pk_bf16_f32 v73, v196, v197
	v_sub_f32_e32 v78, v112, v159
	v_sub_f32_e32 v112, v113, v159
	s_waitcnt lgkmcnt(6)
	v_mfma_f32_32x32x16_bf16 v[48:63], v[66:69], v[70:73], v[48:63]
	ds_read_b64 v[66:67], v184 offset:32
	ds_read_b64 v[68:69], v184 offset:48
	v_sub_f32_e32 v113, v114, v159
	v_sub_f32_e32 v114, v115, v159
	v_sub_f32_e32 v115, v116, v159
	v_sub_f32_e32 v160, v117, v159
	v_sub_f32_e32 v161, v118, v159
	v_sub_f32_e32 v189, v119, v159
	v_mfma_f32_32x32x16_bf16 v[80:95], v[24:27], v[142:145], v[80:95]
	v_exp_f32_e32 v117, v112
	v_exp_f32_e32 v118, v113
	v_exp_f32_e32 v119, v114
	v_exp_f32_e32 v214, v115
	ds_read_b64 v[112:113], v185 offset:1088
	ds_read_b64 v[114:115], v185 offset:1104
	v_exp_f32_e32 v116, v78
	v_exp_f32_e32 v215, v160
	s_waitcnt lgkmcnt(8)
	v_mfma_f32_32x32x16_bf16 v[16:31], v[4:7], v[0:3], 0
	v_exp_f32_e32 v204, v161
	v_exp_f32_e32 v205, v189
	v_cvt_pk_bf16_f32 v216, v116, v117
	v_cvt_pk_bf16_f32 v217, v118, v119
	v_cvt_pk_bf16_f32 v218, v214, v215
	v_cvt_pk_bf16_f32 v219, v204, v205
	v_sub_f32_e32 v78, v120, v159
	s_waitcnt lgkmcnt(6)
	v_mfma_f32_32x32x16_bf16 v[32:47], v[74:77], v[70:73], v[32:47]
	ds_read_b64 v[74:75], v186 offset:544
	ds_read_b64 v[76:77], v186 offset:560
	v_sub_f32_e32 v124, v124, v159
	v_sub_f32_e32 v160, v126, v159
	v_exp_f32_e32 v210, v124
	v_exp_f32_e32 v206, v78
	v_exp_f32_e32 v212, v160
	s_waitcnt lgkmcnt(6)
	v_mfma_f32_32x32x16_bf16 v[0:15], v[8:11], v[0:3], 0
	s_waitcnt lgkmcnt(4)
	v_mfma_f32_32x32x16_bf16 v[16:31], v[66:69], v[70:73], v[16:31]
	v_lshl_add_u64 v[66:67], s[70:71], 0, v[150:151]
	v_lshl_add_u64 v[68:69], s[70:71], 0, v[154:155]
	v_lshl_add_u64 v[66:67], v[66:67], 0, v[152:153]
	s_waitcnt lgkmcnt(0)
	v_mfma_f32_32x32x16_bf16 v[0:15], v[74:77], v[70:73], v[0:15]
	v_lshl_add_u64 v[70:71], v[68:69], 0, v[156:157]
	global_load_dwordx4 v[66:69], v[66:67], off
	s_nop 0
	global_load_dwordx4 v[70:73], v[70:71], off
	ds_read_b64 v[150:151], v187 offset:1600
	ds_read_b64 v[152:153], v187 offset:1616
	v_mfma_f32_32x32x16_bf16 v[48:63], v[112:115], v[216:219], v[48:63]
	global_load_dwordx4 v[74:77], v[172:173], off offset:256
	global_load_dwordx4 v[112:115], v[174:175], off offset:256
	ds_read_b64 v[154:155], v184 offset:64
	ds_read_b64 v[156:157], v184 offset:80
	s_waitcnt lgkmcnt(2)
	v_mfma_f32_32x32x16_bf16 v[32:47], v[150:153], v[216:219], v[32:47]
	v_sub_f32_e32 v150, v121, v159
	v_sub_f32_e32 v151, v122, v159
	v_sub_f32_e32 v152, v123, v159
	ds_read_b64 v[120:121], v186 offset:576
	ds_read_b64 v[122:123], v186 offset:592
	v_sub_f32_e32 v153, v125, v159
	v_exp_f32_e32 v207, v150
	v_exp_f32_e32 v208, v151
	s_waitcnt lgkmcnt(2)
	v_mfma_f32_32x32x16_bf16 v[16:31], v[154:157], v[216:219], v[16:31]
	v_sub_f32_e32 v154, v127, v159
	ds_read_b64 v[124:125], v185 offset:1120
	ds_read_b64 v[126:127], v185 offset:1136
	v_exp_f32_e32 v209, v152
	v_exp_f32_e32 v211, v153
	v_exp_f32_e32 v213, v154
	s_waitcnt lgkmcnt(2)
	v_mfma_f32_32x32x16_bf16 v[0:15], v[120:123], v[216:219], v[0:15]
	v_cvt_pk_bf16_f32 v120, v206, v207
	v_cvt_pk_bf16_f32 v121, v208, v209
	v_cvt_pk_bf16_f32 v122, v210, v211
	v_cvt_pk_bf16_f32 v123, v212, v213
	s_waitcnt lgkmcnt(0)
	s_nop 0
	v_mfma_f32_32x32x16_bf16 v[48:63], v[124:127], v[120:123], v[48:63]
	ds_read_b64 v[124:125], v187 offset:1632
	ds_read_b64 v[126:127], v187 offset:1648
	s_waitcnt lgkmcnt(0)
	v_mfma_f32_32x32x16_bf16 v[32:47], v[124:127], v[120:123], v[32:47]
	ds_read_b64 v[124:125], v184 offset:96
	ds_read_b64 v[126:127], v184 offset:112
	s_waitcnt lgkmcnt(0)
	v_mfma_f32_32x32x16_bf16 v[16:31], v[124:127], v[120:123], v[16:31]
	ds_read_b64 v[124:125], v186 offset:608
	ds_read_b64 v[126:127], v186 offset:624
	s_nop 15
	s_nop 7
	s_nop 0
	v_max3_f32 v78, v80, v81, v96
	s_nop 0
	v_max3_f32 v78, v78, v97, v82
	s_nop 0
	v_max3_f32 v78, v78, v98, v98
	s_waitcnt lgkmcnt(0)
	v_mfma_f32_32x32x16_bf16 v[0:15], v[124:127], v[120:123], v[0:15]
	v_max3_f32 v78, v78, v83, v99
	s_nop 0
	v_max3_f32 v78, v78, v84, v100
	s_nop 0
	v_max3_f32 v78, v78, v85, v101
	s_nop 0
	v_max3_f32 v78, v78, v86, v102
	s_nop 0
	v_max3_f32 v78, v78, v87, v103
	s_nop 0
	v_max3_f32 v78, v78, v88, v104
	s_nop 0
	v_max3_f32 v78, v78, v89, v105
	s_nop 0
	v_max3_f32 v78, v78, v90, v106
	s_nop 0
	v_max3_f32 v78, v78, v91, v107
	s_nop 0
	v_max3_f32 v78, v78, v92, v108
	s_nop 0
	v_max3_f32 v78, v78, v93, v109
	s_nop 0
	v_max3_f32 v78, v78, v94, v110
	s_nop 0
	v_max3_f32 v78, v78, v95, v111
	ds_bpermute_b32 v150, v163, v78
	v_max_f32_e32 v78, v78, v78
	s_waitcnt lgkmcnt(0)
	v_max_f32_e32 v120, v150, v150
	v_max_f32_e32 v78, v78, v120
	v_cmp_lt_f32_e32 vcc, 0x41000000, v78
	s_cbranch_vccz .LBB0_1185
	v_max_f32_e32 v64, v78, v78
	v_max_f32_e32 v120, 0, v64
	v_exp_f32_e64 v78, -v120
	v_add_f32_e32 v181, v181, v120
	v_xor_b32_e32 v64, 0x80000000, v181
	v_pk_add_f32 v[80:81], v[80:81], v[120:121] op_sel_hi:[1,0] neg_lo:[0,1] neg_hi:[0,1]
	v_pk_add_f32 v[96:97], v[96:97], v[120:121] op_sel_hi:[1,0] neg_lo:[0,1] neg_hi:[0,1]
	v_pk_add_f32 v[82:83], v[82:83], v[120:121] op_sel_hi:[1,0] neg_lo:[0,1] neg_hi:[0,1]
	v_pk_add_f32 v[98:99], v[98:99], v[120:121] op_sel_hi:[1,0] neg_lo:[0,1] neg_hi:[0,1]
	v_pk_add_f32 v[84:85], v[84:85], v[120:121] op_sel_hi:[1,0] neg_lo:[0,1] neg_hi:[0,1]
	v_pk_add_f32 v[100:101], v[100:101], v[120:121] op_sel_hi:[1,0] neg_lo:[0,1] neg_hi:[0,1]
	v_pk_add_f32 v[86:87], v[86:87], v[120:121] op_sel_hi:[1,0] neg_lo:[0,1] neg_hi:[0,1]
	v_pk_add_f32 v[102:103], v[102:103], v[120:121] op_sel_hi:[1,0] neg_lo:[0,1] neg_hi:[0,1]
	v_pk_add_f32 v[88:89], v[88:89], v[120:121] op_sel_hi:[1,0] neg_lo:[0,1] neg_hi:[0,1]
	v_pk_add_f32 v[104:105], v[104:105], v[120:121] op_sel_hi:[1,0] neg_lo:[0,1] neg_hi:[0,1]
	v_pk_add_f32 v[90:91], v[90:91], v[120:121] op_sel_hi:[1,0] neg_lo:[0,1] neg_hi:[0,1]
	v_pk_add_f32 v[106:107], v[106:107], v[120:121] op_sel_hi:[1,0] neg_lo:[0,1] neg_hi:[0,1]
	v_pk_add_f32 v[92:93], v[92:93], v[120:121] op_sel_hi:[1,0] neg_lo:[0,1] neg_hi:[0,1]
	v_pk_add_f32 v[108:109], v[108:109], v[120:121] op_sel_hi:[1,0] neg_lo:[0,1] neg_hi:[0,1]
	v_pk_add_f32 v[94:95], v[94:95], v[120:121] op_sel_hi:[1,0] neg_lo:[0,1] neg_hi:[0,1]
	v_pk_add_f32 v[110:111], v[110:111], v[120:121] op_sel_hi:[1,0] neg_lo:[0,1] neg_hi:[0,1]
	v_cmp_neq_f32_e32 vcc, 1.0, v78
	s_cbranch_vccz .LBB0_1120

.LBB0_1121:
	s_mov_b32 s70, s66
	s_mov_b32 s66, s71
	s_mul_i32 s71, s71, 0x9000
	v_add_u32_e32 v169, s71, v180
	ds_read_b128 v[96:99], v169
	ds_read_b128 v[170:173], v169 offset:8704
	s_mul_i32 s71, s70, 0x9000
	s_waitcnt lgkmcnt(0)
	v_mfma_f32_32x32x16_bf16 v[80:95], v[96:99], v[130:133], v[64:79]
	v_mov_b64_e32 v[110:111], v[78:79]
	v_mov_b64_e32 v[108:109], v[76:77]
	v_mov_b64_e32 v[106:107], v[74:75]
	v_mov_b64_e32 v[104:105], v[72:73]
	v_mov_b64_e32 v[102:103], v[70:71]
	v_mov_b64_e32 v[100:101], v[68:69]
	v_mov_b64_e32 v[98:99], v[66:67]
	v_mov_b64_e32 v[96:97], v[64:65]
	s_waitcnt lgkmcnt(0)
	s_nop 0
	v_mfma_f32_32x32x16_bf16 v[96:111], v[170:173], v[130:133], v[96:111]
	ds_read_b128 v[170:173], v169 offset:32
	s_waitcnt lgkmcnt(0)
	v_mfma_f32_32x32x16_bf16 v[80:95], v[170:173], v[134:137], v[80:95]
	ds_read_b128 v[170:173], v169 offset:8736
	s_waitcnt lgkmcnt(0)
	v_mfma_f32_32x32x16_bf16 v[96:111], v[170:173], v[134:137], v[96:111]
	ds_read_b128 v[170:173], v169 offset:64
	s_waitcnt lgkmcnt(0)
	v_mfma_f32_32x32x16_bf16 v[80:95], v[170:173], v[138:141], v[80:95]
	ds_read_b128 v[170:173], v169 offset:8768
	s_waitcnt lgkmcnt(0)
	v_mfma_f32_32x32x16_bf16 v[96:111], v[170:173], v[138:141], v[96:111]
	ds_read_b128 v[170:173], v169 offset:96
	s_waitcnt lgkmcnt(0)
	v_mfma_f32_32x32x16_bf16 v[80:95], v[170:173], v[142:145], v[80:95]
	ds_read_b128 v[170:173], v169 offset:8800
	v_add_u32_e32 v169, s71, v188
	v_add_u32_e32 v174, 0x4000, v169
	v_add_u32_e32 v175, 0x5000, v169
	v_add_u32_e32 v190, 0x6800, v169
	v_add_u32_e32 v169, 0x7800, v169
	s_waitcnt lgkmcnt(0)
	v_mfma_f32_32x32x16_bf16 v[96:111], v[170:173], v[142:145], v[96:111]
	ds_read_b64 v[170:171], v174 offset:1024
	ds_read_b64 v[172:173], v174 offset:1040
	s_waitcnt lgkmcnt(0)
	v_mfma_f32_32x32x16_bf16 v[48:63], v[170:173], v[158:161], v[48:63]
	ds_read_b64 v[170:171], v175 offset:1536
	ds_read_b64 v[172:173], v175 offset:1552
	s_waitcnt lgkmcnt(0)
	v_mfma_f32_32x32x16_bf16 v[32:47], v[170:173], v[158:161], v[32:47]
	ds_read_b64 v[170:171], v190 offset:0
	ds_read_b64 v[172:173], v190 offset:16
	s_waitcnt lgkmcnt(0)
	v_mfma_f32_32x32x16_bf16 v[16:31], v[170:173], v[158:161], v[16:31]
	ds_read_b64 v[170:171], v169 offset:512
	ds_read_b64 v[172:173], v169 offset:528
	s_waitcnt lgkmcnt(0)
	v_mfma_f32_32x32x16_bf16 v[0:15], v[170:173], v[158:161], v[0:15]
	ds_read_b64 v[158:159], v174 offset:1056
	ds_read_b64 v[160:161], v174 offset:1072
	s_waitcnt lgkmcnt(0)
	v_mfma_f32_32x32x16_bf16 v[48:63], v[158:161], v[154:157], v[48:63]
	ds_read_b64 v[158:159], v175 offset:1568
	ds_read_b64 v[160:161], v175 offset:1584
	s_waitcnt lgkmcnt(0)
	v_mfma_f32_32x32x16_bf16 v[32:47], v[158:161], v[154:157], v[32:47]
	ds_read_b64 v[158:159], v190 offset:32
	ds_read_b64 v[160:161], v190 offset:48
	s_waitcnt lgkmcnt(0)
	v_mfma_f32_32x32x16_bf16 v[16:31], v[158:161], v[154:157], v[16:31]
	ds_read_b64 v[158:159], v169 offset:544
	ds_read_b64 v[160:161], v169 offset:560
	s_waitcnt lgkmcnt(0)
	v_mfma_f32_32x32x16_bf16 v[0:15], v[158:161], v[154:157], v[0:15]
	ds_read_b64 v[154:155], v174 offset:1088
	ds_read_b64 v[156:157], v174 offset:1104
	s_waitcnt lgkmcnt(0)
	v_mfma_f32_32x32x16_bf16 v[48:63], v[154:157], v[150:153], v[48:63]
	ds_read_b64 v[154:155], v175 offset:1600
	ds_read_b64 v[156:157], v175 offset:1616
	s_waitcnt lgkmcnt(0)
	v_mfma_f32_32x32x16_bf16 v[32:47], v[154:157], v[150:153], v[32:47]
	ds_read_b64 v[154:155], v190 offset:64
	ds_read_b64 v[156:157], v190 offset:80
	s_waitcnt lgkmcnt(0)
	v_mfma_f32_32x32x16_bf16 v[16:31], v[154:157], v[150:153], v[16:31]
	ds_read_b64 v[154:155], v169 offset:576
	ds_read_b64 v[156:157], v169 offset:592
	s_waitcnt lgkmcnt(0)
	v_mfma_f32_32x32x16_bf16 v[0:15], v[154:157], v[150:153], v[0:15]
	ds_read_b64 v[150:151], v174 offset:1120
	ds_read_b64 v[152:153], v174 offset:1136
	ds_read_b64 v[154:155], v175 offset:1632
	ds_read_b64 v[156:157], v175 offset:1648
	ds_read_b64 v[158:159], v190 offset:96
	ds_read_b64 v[160:161], v190 offset:112
	ds_read_b64 v[170:171], v169 offset:608
	ds_read_b64 v[172:173], v169 offset:624
	s_nop 15
	s_nop 7
	s_waitcnt lgkmcnt(6)
	v_mfma_f32_32x32x16_bf16 v[48:63], v[150:153], v[146:149], v[48:63]
	v_max3_f32 v150, v80, v81, v96
	s_nop 0
	v_max3_f32 v150, v150, v97, v82
	s_nop 0
	v_max3_f32 v150, v150, v98, v98
	s_nop 0
	v_max3_f32 v150, v150, v83, v99
	s_waitcnt lgkmcnt(4)
	v_mfma_f32_32x32x16_bf16 v[32:47], v[154:157], v[146:149], v[32:47]
	v_max3_f32 v150, v150, v84, v100
	s_nop 0
	v_max3_f32 v150, v150, v85, v101
	s_nop 0
	v_max3_f32 v150, v150, v86, v102
	s_nop 0
	v_max3_f32 v150, v150, v87, v103
	s_waitcnt lgkmcnt(2)
	v_mfma_f32_32x32x16_bf16 v[16:31], v[158:161], v[146:149], v[16:31]
	v_max3_f32 v150, v150, v88, v104
	s_nop 0
	v_max3_f32 v150, v150, v89, v105
	s_nop 0
	v_max3_f32 v150, v150, v90, v106
	s_nop 0
	v_max3_f32 v150, v150, v91, v107
	s_waitcnt lgkmcnt(0)
	v_mfma_f32_32x32x16_bf16 v[0:15], v[170:173], v[146:149], v[0:15]
	v_max3_f32 v150, v150, v92, v108
	s_nop 0
	v_max3_f32 v150, v150, v93, v109
	s_nop 0
	v_max3_f32 v150, v150, v94, v110
	s_nop 0
	v_max3_f32 v150, v150, v95, v111
	ds_bpermute_b32 v151, v163, v150
	v_max_f32_e32 v150, v150, v150
	s_waitcnt lgkmcnt(0)
	v_max_f32_e32 v151, v151, v151
	v_max_f32_e32 v150, v150, v151
	v_cmp_lt_f32_e32 vcc, 0x41000000, v150
	s_cbranch_vccz .LBB0_1128
	v_max_f32_e32 v64, v150, v150
	v_max_f32_e32 v66, 0, v64
	v_exp_f32_e64 v146, -v66
	v_add_f32_e32 v181, v181, v66
	v_xor_b32_e32 v64, 0x80000000, v181
	v_pk_add_f32 v[80:81], v[80:81], v[66:67] op_sel_hi:[1,0] neg_lo:[0,1] neg_hi:[0,1]
	v_pk_add_f32 v[96:97], v[96:97], v[66:67] op_sel_hi:[1,0] neg_lo:[0,1] neg_hi:[0,1]
	v_pk_add_f32 v[82:83], v[82:83], v[66:67] op_sel_hi:[1,0] neg_lo:[0,1] neg_hi:[0,1]
	v_pk_add_f32 v[98:99], v[98:99], v[66:67] op_sel_hi:[1,0] neg_lo:[0,1] neg_hi:[0,1]
	v_pk_add_f32 v[84:85], v[84:85], v[66:67] op_sel_hi:[1,0] neg_lo:[0,1] neg_hi:[0,1]
	v_pk_add_f32 v[100:101], v[100:101], v[66:67] op_sel_hi:[1,0] neg_lo:[0,1] neg_hi:[0,1]
	v_pk_add_f32 v[86:87], v[86:87], v[66:67] op_sel_hi:[1,0] neg_lo:[0,1] neg_hi:[0,1]
	v_pk_add_f32 v[102:103], v[102:103], v[66:67] op_sel_hi:[1,0] neg_lo:[0,1] neg_hi:[0,1]
	v_pk_add_f32 v[88:89], v[88:89], v[66:67] op_sel_hi:[1,0] neg_lo:[0,1] neg_hi:[0,1]
	v_pk_add_f32 v[104:105], v[104:105], v[66:67] op_sel_hi:[1,0] neg_lo:[0,1] neg_hi:[0,1]
	v_pk_add_f32 v[90:91], v[90:91], v[66:67] op_sel_hi:[1,0] neg_lo:[0,1] neg_hi:[0,1]
	v_pk_add_f32 v[106:107], v[106:107], v[66:67] op_sel_hi:[1,0] neg_lo:[0,1] neg_hi:[0,1]
	v_pk_add_f32 v[92:93], v[92:93], v[66:67] op_sel_hi:[1,0] neg_lo:[0,1] neg_hi:[0,1]
	v_pk_add_f32 v[108:109], v[108:109], v[66:67] op_sel_hi:[1,0] neg_lo:[0,1] neg_hi:[0,1]
	v_pk_add_f32 v[94:95], v[94:95], v[66:67] op_sel_hi:[1,0] neg_lo:[0,1] neg_hi:[0,1]
	v_pk_add_f32 v[110:111], v[110:111], v[66:67] op_sel_hi:[1,0] neg_lo:[0,1] neg_hi:[0,1]
	v_mov_b32_e32 v65, v64
	v_mov_b32_e32 v66, v64
	v_mov_b32_e32 v67, v64
	v_mov_b32_e32 v68, v64
	v_mov_b32_e32 v69, v64
	v_mov_b32_e32 v70, v64
	v_mov_b32_e32 v71, v64
	v_mov_b32_e32 v72, v64
	v_mov_b32_e32 v73, v64
	v_mov_b32_e32 v74, v64
	v_mov_b32_e32 v75, v64
	v_mov_b32_e32 v76, v64
	v_mov_b32_e32 v77, v64
	v_mov_b32_e32 v78, v64
	v_mov_b32_e32 v79, v64
	v_cmp_neq_f32_e32 vcc, 1.0, v146
	s_cbranch_vccz .LBB0_1124

.LBB0_1132:
	ds_read_b64 v[64:65], v185 offset:1024
	ds_read_b64 v[66:67], v185 offset:1040
	ds_bpermute_b32 v81, v163, v80
	s_add_i32 s21, s21, 0
	s_cmp_eq_u32 s64, 1
	s_waitcnt lgkmcnt(0)
	v_mfma_f32_32x32x16_bf16 v[48:63], v[64:67], v[158:161], v[48:63]
	ds_read_b64 v[64:65], v187 offset:1536
	ds_read_b64 v[66:67], v187 offset:1552
	s_waitcnt lgkmcnt(0)
	v_mfma_f32_32x32x16_bf16 v[32:47], v[64:67], v[158:161], v[32:47]
	ds_read_b64 v[64:65], v184 offset:0
	ds_read_b64 v[66:67], v184 offset:16
	s_waitcnt lgkmcnt(0)
	v_mfma_f32_32x32x16_bf16 v[16:31], v[64:67], v[158:161], v[16:31]
	ds_read_b64 v[64:65], v186 offset:512
	ds_read_b64 v[66:67], v186 offset:528
	s_waitcnt lgkmcnt(0)
	v_mfma_f32_32x32x16_bf16 v[0:15], v[64:67], v[158:161], v[0:15]
	ds_read_b64 v[64:65], v185 offset:1056
	ds_read_b64 v[66:67], v185 offset:1072
	s_waitcnt lgkmcnt(0)
	v_mfma_f32_32x32x16_bf16 v[48:63], v[64:67], v[154:157], v[48:63]
	ds_read_b64 v[64:65], v187 offset:1568
	ds_read_b64 v[66:67], v187 offset:1584
	s_waitcnt lgkmcnt(0)
	v_mfma_f32_32x32x16_bf16 v[32:47], v[64:67], v[154:157], v[32:47]
	ds_read_b64 v[64:65], v184 offset:32
	ds_read_b64 v[66:67], v184 offset:48
	s_waitcnt lgkmcnt(0)
	v_mfma_f32_32x32x16_bf16 v[16:31], v[64:67], v[154:157], v[16:31]
	ds_read_b64 v[64:65], v186 offset:544
	ds_read_b64 v[66:67], v186 offset:560
	s_waitcnt lgkmcnt(0)
	v_mfma_f32_32x32x16_bf16 v[0:15], v[64:67], v[154:157], v[0:15]
	ds_read_b64 v[64:65], v185 offset:1088
	ds_read_b64 v[66:67], v185 offset:1104
	s_waitcnt lgkmcnt(0)
	v_mfma_f32_32x32x16_bf16 v[48:63], v[64:67], v[150:153], v[48:63]
	ds_read_b64 v[64:65], v187 offset:1600
	ds_read_b64 v[66:67], v187 offset:1616
	s_waitcnt lgkmcnt(0)
	v_mfma_f32_32x32x16_bf16 v[32:47], v[64:67], v[150:153], v[32:47]
	ds_read_b64 v[64:65], v184 offset:64
	ds_read_b64 v[66:67], v184 offset:80
	s_waitcnt lgkmcnt(0)
	v_mfma_f32_32x32x16_bf16 v[16:31], v[64:67], v[150:153], v[16:31]
	ds_read_b64 v[64:65], v186 offset:576
	ds_read_b64 v[66:67], v186 offset:592
	s_waitcnt lgkmcnt(0)
	v_mfma_f32_32x32x16_bf16 v[0:15], v[64:67], v[150:153], v[0:15]
	ds_read_b64 v[64:65], v185 offset:1120
	ds_read_b64 v[66:67], v185 offset:1136
	ds_read_b64 v[68:69], v187 offset:1632
	ds_read_b64 v[70:71], v187 offset:1648
	ds_read_b64 v[72:73], v184 offset:96
	ds_read_b64 v[74:75], v184 offset:112
	ds_read_b64 v[76:77], v186 offset:608
	ds_read_b64 v[78:79], v186 offset:624
	s_waitcnt lgkmcnt(0)
	s_barrier
	v_mfma_f32_32x32x16_bf16 v[48:63], v[64:67], v[146:149], v[48:63]
	v_add_f32_e32 v64, v80, v81
	v_div_scale_f32 v65, s[24:25], v64, v64, 1.0
	v_rcp_f32_e32 v66, v65
	s_nop 0
	v_fma_f32 v67, -v65, v66, 1.0
	v_mfma_f32_32x32x16_bf16 v[32:47], v[68:71], v[146:149], v[32:47]
	v_fmac_f32_e32 v66, v67, v66
	v_div_scale_f32 v67, vcc, 1.0, v64, 1.0
	v_mul_f32_e32 v68, v67, v66
	v_fma_f32 v69, -v65, v68, v67
	v_fmac_f32_e32 v68, v69, v66
	v_fma_f32 v65, -v65, v68, v67
	v_mfma_f32_32x32x16_bf16 v[16:31], v[72:75], v[146:149], v[16:31]
	v_div_fmas_f32 v65, v65, v66, v68
	v_div_fixup_f32 v66, v65, v64, 1.0
	v_lshl_add_u32 v64, v189, 2, s21
	v_mfma_f32_32x32x16_bf16 v[0:15], v[76:79], v[146:149], v[0:15]
	s_cbranch_scc0 .LBB0_1134
	v_mul_f32_e32 v65, v182, v66
	v_mul_f32_e32 v67, v48, v65
	v_mul_f32_e32 v68, v49, v65
	ds_write2st64_b32 v64, v67, v68 offset1:1
	v_mul_f32_e32 v67, v50, v65
	v_mul_f32_e32 v68, v51, v65
	ds_write2st64_b32 v64, v67, v68 offset0:2 offset1:3
	v_mul_f32_e32 v67, v52, v65
	v_mul_f32_e32 v68, v53, v65
	ds_write2st64_b32 v64, v67, v68 offset0:4 offset1:5
	v_mul_f32_e32 v67, v54, v65
	v_mul_f32_e32 v68, v55, v65
	ds_write2st64_b32 v64, v67, v68 offset0:6 offset1:7
	v_mul_f32_e32 v67, v56, v65
	v_mul_f32_e32 v68, v57, v65
	ds_write2st64_b32 v64, v67, v68 offset0:8 offset1:9
	v_mul_f32_e32 v67, v58, v65
	v_mul_f32_e32 v68, v59, v65
	ds_write2st64_b32 v64, v67, v68 offset0:10 offset1:11
	v_mul_f32_e32 v67, v60, v65
	v_mul_f32_e32 v68, v61, v65
	ds_write2st64_b32 v64, v67, v68 offset0:12 offset1:13
	v_mul_f32_e32 v67, v62, v65
	v_mul_f32_e32 v68, v63, v65
	ds_write2st64_b32 v64, v67, v68 offset0:14 offset1:15
	v_mul_f32_e32 v67, v32, v65
	v_mul_f32_e32 v68, v33, v65
	ds_write2st64_b32 v64, v67, v68 offset0:16 offset1:17
	v_mul_f32_e32 v67, v34, v65
	v_mul_f32_e32 v68, v35, v65
	ds_write2st64_b32 v64, v67, v68 offset0:18 offset1:19
	v_mul_f32_e32 v67, v36, v65
	v_mul_f32_e32 v68, v37, v65
	ds_write2st64_b32 v64, v67, v68 offset0:20 offset1:21
	v_mul_f32_e32 v67, v38, v65
	v_mul_f32_e32 v68, v39, v65
	ds_write2st64_b32 v64, v67, v68 offset0:22 offset1:23
	v_mul_f32_e32 v67, v40, v65
	v_mul_f32_e32 v68, v41, v65
	ds_write2st64_b32 v64, v67, v68 offset0:24 offset1:25
	v_mul_f32_e32 v67, v42, v65
	v_mul_f32_e32 v68, v43, v65
	ds_write2st64_b32 v64, v67, v68 offset0:26 offset1:27
	v_mul_f32_e32 v67, v44, v65
	v_mul_f32_e32 v68, v45, v65
	ds_write2st64_b32 v64, v67, v68 offset0:28 offset1:29
	v_mul_f32_e32 v67, v46, v65
	v_mul_f32_e32 v68, v47, v65
	ds_write2st64_b32 v64, v67, v68 offset0:30 offset1:31
	v_mul_f32_e32 v67, v16, v65
	v_mul_f32_e32 v68, v17, v65
	ds_write2st64_b32 v64, v67, v68 offset0:32 offset1:33
	v_mul_f32_e32 v67, v18, v65
	v_mul_f32_e32 v68, v19, v65
	ds_write2st64_b32 v64, v67, v68 offset0:34 offset1:35
	v_mul_f32_e32 v67, v20, v65
	v_mul_f32_e32 v68, v21, v65
	ds_write2st64_b32 v64, v67, v68 offset0:36 offset1:37
	v_mul_f32_e32 v67, v22, v65
	v_mul_f32_e32 v68, v23, v65
	ds_write2st64_b32 v64, v67, v68 offset0:38 offset1:39
	v_mul_f32_e32 v67, v24, v65
	v_mul_f32_e32 v68, v25, v65
	ds_write2st64_b32 v64, v67, v68 offset0:40 offset1:41
	v_mul_f32_e32 v67, v26, v65
	v_mul_f32_e32 v68, v27, v65
	ds_write2st64_b32 v64, v67, v68 offset0:42 offset1:43
	v_mul_f32_e32 v67, v28, v65
	v_mul_f32_e32 v68, v29, v65
	ds_write2st64_b32 v64, v67, v68 offset0:44 offset1:45
	v_mul_f32_e32 v67, v30, v65
	v_mul_f32_e32 v68, v31, v65
	ds_write2st64_b32 v64, v67, v68 offset0:46 offset1:47
	v_mul_f32_e32 v67, v0, v65
	v_mul_f32_e32 v68, v1, v65
	ds_write2st64_b32 v64, v67, v68 offset0:48 offset1:49
	v_mul_f32_e32 v67, v2, v65
	v_mul_f32_e32 v68, v3, v65
	ds_write2st64_b32 v64, v67, v68 offset0:50 offset1:51
	v_mul_f32_e32 v67, v4, v65
	v_mul_f32_e32 v68, v5, v65
	ds_write2st64_b32 v64, v67, v68 offset0:52 offset1:53
	v_mul_f32_e32 v67, v6, v65
	v_mul_f32_e32 v68, v7, v65
	ds_write2st64_b32 v64, v67, v68 offset0:54 offset1:55
	v_mul_f32_e32 v67, v8, v65
	v_mul_f32_e32 v68, v9, v65
	ds_write2st64_b32 v64, v67, v68 offset0:56 offset1:57
	v_mul_f32_e32 v67, v10, v65
	v_mul_f32_e32 v68, v11, v65
	ds_write2st64_b32 v64, v67, v68 offset0:58 offset1:59
	v_mul_f32_e32 v67, v12, v65
	v_mul_f32_e32 v68, v13, v65
	ds_write2st64_b32 v64, v67, v68 offset0:60 offset1:61
	v_mul_f32_e32 v67, v14, v65
	v_mul_f32_e32 v65, v15, v65
	ds_write2st64_b32 v64, v67, v65 offset0:62 offset1:63

.LBB0_1139:
	s_lshr_b32 s19, s62, 3
	s_lshl_b32 s20, s62, 7
	s_lshl_b32 s18, s19, 8
	s_and_b32 s20, s20, 0x80
	s_or_b32 s18, s18, s20
	s_bfe_u32 s24, s62, 0x10002
	s_lshl_b32 s20, s18, 10
	s_add_u32 s20, s47, s20
	s_addc_u32 s21, s48, 0
	s_lshl_b32 s23, s62, 6
	s_lshl_b32 s22, s24, 8
	s_and_b32 s23, s23, 0x80
	s_or_b32 s26, s22, s23
	s_or_b32 s27, s26, 64
	s_lshl_b32 s19, s19, 16
	s_add_u32 s22, s49, s19
	s_addc_u32 s23, s50, 0
	s_lshl_b32 s25, s24, 7
	s_add_u32 s22, s22, s25
	v_mov_b32_e32 v14, v244
	s_addc_u32 s23, s23, 0
	s_add_u32 s19, s51, s19
	v_ashrrev_i32_e32 v0, 31, v14
	v_lshrrev_b32_e32 v0, 29, v0
	s_addc_u32 s25, s54, 0
	s_lshl_b32 s24, s24, 15
	v_add_u32_e32 v0, v14, v0
	s_add_u32 s24, s19, s24
	v_readfirstlane_b32 s19, v14
	v_ashrrev_i32_e32 v10, 3, v0
	v_and_b32_e32 v0, -8, v0
	s_addc_u32 s25, s25, 0
	s_lshr_b32 s63, s19, 1
	v_sub_u32_e32 v17, v14, v0
	v_ashrrev_i32_e32 v11, 31, v10
	v_and_b32_e32 v16, 31, v14
	s_and_b32 s63, s63, 0x60
	v_lshlrev_b64 v[0:1], 8, v[10:11]
	v_lshlrev_b32_e32 v2, 3, v17
	v_ashrrev_i32_e32 v12, 3, v14
	s_waitcnt vmcnt(9)
	v_or_b32_e32 v98, s63, v16
	v_lshl_add_u64 v[0:1], s[22:23], 0, v[0:1]
	v_ashrrev_i32_e32 v3, 31, v2
	v_ashrrev_i32_e32 v13, 31, v12
	v_lshlrev_b32_e32 v128, 10, v98
	v_lshl_add_u64 v[96:97], v[2:3], 1, v[0:1]
	v_lshlrev_b64 v[0:1], 9, v[12:13]
	v_lshlrev_b32_e32 v2, 4, v14
	v_lshl_add_u64 v[8:9], s[20:21], 0, v[128:129]
	v_lshl_add_u64 v[0:1], s[24:25], 0, v[0:1]
	v_and_b32_e32 v128, 0x70, v2
	s_waitcnt vmcnt(8)
	v_lshl_add_u64 v[100:101], v[0:1], 0, v[128:129]
	global_load_dwordx4 v[0:3], v[96:97], off
	global_load_dwordx4 v[4:7], v[100:101], off
	s_cmpk_lt_u32 s19, 0x100
	s_cselect_b32 s19, s26, s27
	s_waitcnt vmcnt(3)
	v_bfe_u32 v120, v14, 5, 1
	s_lshl_b32 s68, s19, 1
	v_lshlrev_b32_e32 v14, 4, v120
	v_lshl_add_u64 v[8:9], v[8:9], 0, s[68:69]
	v_mov_b32_e32 v15, v129
	v_lshl_add_u64 v[8:9], v[8:9], 0, v[14:15]
	global_load_dwordx4 v[80:83], v[8:9], off
	global_load_dwordx4 v[84:87], v[8:9], off offset:32
	global_load_dwordx4 v[88:91], v[8:9], off offset:64
	global_load_dwordx4 v[92:95], v[8:9], off offset:96
	s_movk_i32 s19, 0x90
	v_mad_u32_u24 v26, v16, s19, 0
	v_mul_lo_u32 v123, v10, s19
	s_waitcnt vmcnt(6)
	v_lshlrev_b32_e32 v124, 4, v17
	v_mul_lo_u32 v121, v12, s19
	v_add_u32_e32 v122, v26, v14
	v_add3_u32 v24, 0, v123, v124
	v_add3_u32 v25, 0, v121, v128
	s_movk_i32 s19, 0x4000
	v_and_b32_e32 v32, 64, v248
	v_xor_b32_e32 v27, 32, v248
	v_add_u32_e32 v32, 64, v32
	v_lshl_add_u32 v127, v120, 3, v26
	v_add_u32_e32 v126, 0x4000, v127
	v_add_u32_e32 v131, 0x5000, v127
	s_waitcnt vmcnt(5)
	ds_write_b128 v24, v[0:3]
	s_waitcnt vmcnt(4)
	ds_write_b128 v25, v[4:7] offset:17408
	s_waitcnt lgkmcnt(0)
	s_barrier
	ds_read_b128 v[0:3], v122
	ds_read_b128 v[16:19], v122 offset:32
	s_waitcnt vmcnt(3) lgkmcnt(1)
	v_mfma_f32_32x32x16_bf16 v[0:15], v[0:3], v[80:83], 0
	ds_read_b128 v[20:23], v122 offset:4608
	ds_read_b128 v[28:31], v122 offset:4640
	s_waitcnt lgkmcnt(1)
	v_mfma_f32_32x32x16_bf16 v[48:63], v[20:23], v[80:83], 0
	s_waitcnt vmcnt(2)
	v_mfma_f32_32x32x16_bf16 v[0:15], v[16:19], v[84:87], v[0:15]
	ds_read_b128 v[16:19], v122 offset:64
	ds_read_b128 v[20:23], v122 offset:96
	s_waitcnt lgkmcnt(2)
	v_mfma_f32_32x32x16_bf16 v[48:63], v[28:31], v[84:87], v[48:63]
	s_waitcnt vmcnt(1) lgkmcnt(1)
	v_mfma_f32_32x32x16_bf16 v[0:15], v[16:19], v[88:91], v[0:15]
	ds_read_b128 v[16:19], v122 offset:4672
	ds_read_b128 v[28:31], v122 offset:4704
	s_waitcnt lgkmcnt(1)
	v_mfma_f32_32x32x16_bf16 v[48:63], v[16:19], v[88:91], v[48:63]
	v_add_co_u32_e32 v16, vcc, s19, v96
	s_mov_b32 s19, 0x8000
	s_nop 0
	v_addc_co_u32_e32 v17, vcc, 0, v97, vcc
	global_load_dwordx4 v[16:19], v[16:17], off
	v_cmp_lt_i32_e32 vcc, v27, v32
	s_waitcnt vmcnt(1)
	v_mfma_f32_32x32x16_bf16 v[0:15], v[20:23], v[92:95], v[0:15]
	global_load_dwordx4 v[20:23], v[100:101], off offset:128
	v_cndmask_b32_e32 v27, v248, v27, vcc
	v_lshlrev_b32_e32 v125, 2, v27
	s_waitcnt lgkmcnt(0)
	v_mfma_f32_32x32x16_bf16 v[48:63], v[28:31], v[92:95], v[48:63]
	s_nop 15
	s_nop 7
	s_waitcnt vmcnt(1)
	ds_write_b128 v24, v[16:19] offset:36864
	s_waitcnt vmcnt(0)
	ds_write_b128 v25, v[20:23] offset:54272
	v_max3_f32 v27, v0, v1, v48
	s_waitcnt lgkmcnt(0)
	v_max3_f32 v27, v27, v49, v2
	s_barrier
	v_max3_f32 v27, v27, v50, v50
	s_nop 0
	v_max3_f32 v27, v27, v3, v51
	ds_read_b128 v[16:19], v122 offset:36864
	v_max3_f32 v27, v27, v4, v52
	s_nop 0
	v_max3_f32 v27, v27, v5, v53
	s_nop 0
	v_max3_f32 v27, v27, v6, v54
	s_nop 0
	v_max3_f32 v27, v27, v7, v55
	s_nop 0
	v_max3_f32 v27, v27, v8, v56
	s_nop 0
	v_max3_f32 v27, v27, v9, v57
	s_nop 0
	v_max3_f32 v27, v27, v10, v58
	s_nop 0
	v_max3_f32 v27, v27, v11, v59
	s_nop 0
	v_max3_f32 v27, v27, v12, v60
	s_nop 0
	v_max3_f32 v27, v27, v13, v61
	s_nop 0
	v_max3_f32 v27, v27, v14, v62
	s_nop 0
	v_max3_f32 v27, v27, v15, v63
	ds_bpermute_b32 v28, v125, v27
	v_max_f32_e32 v26, v27, v27
	s_waitcnt lgkmcnt(0)
	v_max_f32_e32 v27, v28, v28
	v_max_f32_e32 v104, v26, v27
	v_add_f32_e32 v130, 0, v104
	v_xor_b32_e32 v32, 0x80000000, v130
	ds_read_b128 v[20:23], v122 offset:41472
	ds_read_b128 v[24:27], v122 offset:36896
	v_mov_b32_e32 v33, v32
	v_mov_b32_e32 v34, v32
	v_mov_b32_e32 v35, v32
	v_mov_b32_e32 v36, v32
	v_mov_b32_e32 v37, v32
	v_mov_b32_e32 v38, v32
	v_mov_b32_e32 v39, v32
	v_mov_b32_e32 v40, v32
	v_mov_b32_e32 v41, v32
	v_mov_b32_e32 v42, v32
	v_mov_b32_e32 v43, v32
	v_mov_b32_e32 v44, v32
	v_mov_b32_e32 v45, v32
	v_mov_b32_e32 v46, v32
	v_mov_b32_e32 v47, v32
	v_sub_f32_e32 v105, v48, v104
	v_sub_f32_e32 v118, v49, v104
	v_mfma_f32_32x32x16_bf16 v[64:79], v[16:19], v[80:83], v[32:47]
	v_mov_b64_e32 v[48:49], v[46:47]
	ds_read_b128 v[16:19], v122 offset:41504
	v_sub_f32_e32 v28, v0, v104
	v_sub_f32_e32 v29, v1, v104
	v_sub_f32_e32 v30, v2, v104
	s_nop 1
	v_mov_b64_e32 v[46:47], v[44:45]
	v_mov_b64_e32 v[44:45], v[42:43]
	v_mov_b64_e32 v[42:43], v[40:41]
	v_mov_b64_e32 v[40:41], v[38:39]
	v_mov_b64_e32 v[38:39], v[36:37]
	v_mov_b64_e32 v[36:37], v[34:35]
	v_mov_b64_e32 v[34:35], v[32:33]
	v_sub_f32_e32 v106, v8, v104
	v_sub_f32_e32 v107, v9, v104
	s_waitcnt lgkmcnt(2)
	v_mfma_f32_32x32x16_bf16 v[34:49], v[20:23], v[80:83], v[34:49]
	v_sub_f32_e32 v20, v3, v104
	ds_read_b128 v[0:3], v122 offset:36928
	v_sub_f32_e32 v108, v10, v104
	v_sub_f32_e32 v109, v11, v104
	v_sub_f32_e32 v21, v4, v104
	v_sub_f32_e32 v22, v5, v104
	v_sub_f32_e32 v23, v6, v104
	s_waitcnt lgkmcnt(1)
	v_mfma_f32_32x32x16_bf16 v[34:49], v[16:19], v[84:87], v[34:49]
	ds_read_b128 v[8:11], v122 offset:41536
	ds_read_b128 v[16:19], v122 offset:36960
	v_sub_f32_e32 v119, v50, v104
	v_sub_f32_e32 v132, v51, v104
	v_sub_f32_e32 v141, v52, v104
	v_sub_f32_e32 v144, v53, v104
	v_sub_f32_e32 v145, v54, v104
	v_sub_f32_e32 v146, v55, v104
	v_mfma_f32_32x32x16_bf16 v[64:79], v[24:27], v[84:87], v[64:79]
	v_sub_f32_e32 v24, v7, v104
	ds_read_b128 v[4:7], v122 offset:41568
	v_sub_f32_e32 v147, v56, v104
	v_sub_f32_e32 v148, v57, v104
	v_sub_f32_e32 v153, v59, v104
	v_sub_f32_e32 v154, v60, v104
	v_sub_f32_e32 v155, v61, v104
	s_waitcnt lgkmcnt(2)
	v_mfma_f32_32x32x16_bf16 v[34:49], v[8:11], v[88:91], v[34:49]
	ds_read_b64 v[8:9], v126 offset:1024
	ds_read_b64 v[10:11], v126 offset:1040
	v_sub_f32_e32 v156, v62, v104
	v_exp_f32_e32 v103, v28
	v_exp_f32_e32 v102, v29
	v_exp_f32_e32 v99, v30
	v_exp_f32_e32 v62, v20
	v_exp_f32_e32 v61, v21
	s_waitcnt lgkmcnt(2)
	v_mfma_f32_32x32x16_bf16 v[34:49], v[4:7], v[92:95], v[34:49]
	v_add_co_u32_e32 v4, vcc, s19, v96
	v_exp_f32_e32 v59, v22
	s_nop 0
	v_addc_co_u32_e32 v5, vcc, 0, v97, vcc
	global_load_dwordx4 v[50:53], v[4:5], off
	global_load_dwordx4 v[54:57], v[100:101], off offset:256
	v_exp_f32_e32 v60, v23
	v_mfma_f32_32x32x16_bf16 v[64:79], v[0:3], v[88:91], v[64:79]
	v_exp_f32_e32 v33, v24
	v_cvt_pk_bf16_f32 v0, v103, v102
	v_cvt_pk_bf16_f32 v1, v99, v62
	v_cvt_pk_bf16_f32 v2, v61, v59
	v_cvt_pk_bf16_f32 v3, v60, v33
	ds_read_b64 v[4:5], v131 offset:1536
	ds_read_b64 v[6:7], v131 offset:1552
	v_exp_f32_e32 v138, v106
	v_exp_f32_e32 v137, v107
	v_exp_f32_e32 v136, v108
	v_exp_f32_e32 v135, v109
	ds_read_b64 v[106:107], v126 offset:1056
	ds_read_b64 v[108:109], v126 offset:1072
	v_mfma_f32_32x32x16_bf16 v[64:79], v[16:19], v[92:95], v[64:79]
	v_sub_f32_e32 v12, v12, v104
	v_sub_f32_e32 v13, v13, v104
	v_sub_f32_e32 v110, v14, v104
	v_sub_f32_e32 v111, v15, v104
	v_exp_f32_e32 v134, v12
	v_exp_f32_e32 v133, v13
	v_exp_f32_e32 v140, v110
	s_waitcnt lgkmcnt(4)
	v_mfma_f32_32x32x16_bf16 v[16:31], v[8:11], v[0:3], 0
	v_exp_f32_e32 v139, v111
	v_cvt_pk_bf16_f32 v110, v138, v137
	v_cvt_pk_bf16_f32 v111, v136, v135
	v_cvt_pk_bf16_f32 v112, v134, v133
	v_cvt_pk_bf16_f32 v113, v140, v139
	ds_read_b64 v[114:115], v131 offset:1568
	ds_read_b64 v[116:117], v131 offset:1584
	v_exp_f32_e32 v152, v105
	s_waitcnt lgkmcnt(4)
	v_mfma_f32_32x32x16_bf16 v[0:15], v[4:7], v[0:3], 0
	v_exp_f32_e32 v151, v118
	v_exp_f32_e32 v150, v119
	v_exp_f32_e32 v143, v132
	v_exp_f32_e32 v142, v141
	v_exp_f32_e32 v141, v144
	v_exp_f32_e32 v145, v145
	v_exp_f32_e32 v144, v146
	s_waitcnt lgkmcnt(2)
	v_mfma_f32_32x32x16_bf16 v[16:31], v[106:109], v[110:113], v[16:31]
	ds_read_b64 v[106:107], v126 offset:1088
	ds_read_b64 v[108:109], v126 offset:1104
	v_sub_f32_e32 v58, v58, v104
	v_exp_f32_e32 v149, v147
	v_exp_f32_e32 v148, v148
	v_exp_f32_e32 v147, v58
	v_exp_f32_e32 v146, v153
	v_exp_f32_e32 v155, v155
	s_waitcnt lgkmcnt(2)
	v_mfma_f32_32x32x16_bf16 v[0:15], v[114:117], v[110:113], v[0:15]
	v_cvt_pk_bf16_f32 v110, v152, v151
	v_cvt_pk_bf16_f32 v111, v150, v143
	v_cvt_pk_bf16_f32 v112, v142, v141
	v_cvt_pk_bf16_f32 v113, v145, v144
	ds_read_b64 v[114:115], v131 offset:1600
	ds_read_b64 v[116:117], v131 offset:1616
	s_waitcnt lgkmcnt(2)
	v_mfma_f32_32x32x16_bf16 v[16:31], v[106:109], v[110:113], v[16:31]
	v_sub_f32_e32 v108, v63, v104
	ds_read_b64 v[104:105], v126 offset:1120
	ds_read_b64 v[106:107], v126 offset:1136
	v_exp_f32_e32 v63, v154
	v_exp_f32_e32 v154, v156
	v_exp_f32_e32 v153, v108
	v_cvt_pk_bf16_f32 v108, v149, v148
	v_cvt_pk_bf16_f32 v109, v147, v146
	s_waitcnt lgkmcnt(2)
	v_mfma_f32_32x32x16_bf16 v[0:15], v[114:117], v[110:113], v[0:15]
	v_cvt_pk_bf16_f32 v110, v63, v155
	v_cvt_pk_bf16_f32 v111, v154, v153
	s_waitcnt lgkmcnt(0)
	s_nop 0
	v_mfma_f32_32x32x16_bf16 v[16:31], v[104:107], v[108:111], v[16:31]
	ds_read_b64 v[104:105], v131 offset:1632
	ds_read_b64 v[106:107], v131 offset:1648
	s_nop 15
	s_nop 7
	s_nop 0
	v_max3_f32 v58, v64, v65, v34
	s_nop 0
	v_max3_f32 v58, v58, v35, v66
	s_nop 0
	v_max3_f32 v58, v58, v36, v36
	s_waitcnt lgkmcnt(0)
	v_mfma_f32_32x32x16_bf16 v[0:15], v[104:107], v[108:111], v[0:15]
	v_max3_f32 v58, v58, v67, v37
	s_nop 0
	v_max3_f32 v58, v58, v68, v38
	s_nop 0
	v_max3_f32 v58, v58, v69, v39
	s_nop 0
	v_max3_f32 v58, v58, v70, v40
	s_nop 0
	v_max3_f32 v58, v58, v71, v41
	s_nop 0
	v_max3_f32 v58, v58, v72, v42
	s_nop 0
	v_max3_f32 v58, v58, v73, v43
	s_nop 0
	v_max3_f32 v58, v58, v74, v44
	s_nop 0
	v_max3_f32 v58, v58, v75, v45
	s_nop 0
	v_max3_f32 v58, v58, v76, v46
	s_nop 0
	v_max3_f32 v58, v58, v77, v47
	s_nop 0
	v_max3_f32 v58, v58, v78, v48
	s_nop 0
	v_max3_f32 v58, v58, v79, v49
	ds_bpermute_b32 v112, v125, v58
	v_max_f32_e32 v58, v58, v58
	s_waitcnt lgkmcnt(0)
	v_max_f32_e32 v104, v112, v112
	v_max_f32_e32 v58, v58, v104
	v_cmp_lt_f32_e32 vcc, 0x41000000, v58
	s_cbranch_vccz .LBB0_1163
	v_max_f32_e32 v32, v58, v58
	v_max_f32_e32 v104, 0, v32
	v_exp_f32_e64 v58, -v104
	v_add_f32_e32 v130, v130, v104
	v_xor_b32_e32 v32, 0x80000000, v130
	v_pk_add_f32 v[64:65], v[64:65], v[104:105] op_sel_hi:[1,0] neg_lo:[0,1] neg_hi:[0,1]
	v_pk_add_f32 v[34:35], v[34:35], v[104:105] op_sel_hi:[1,0] neg_lo:[0,1] neg_hi:[0,1]
	v_pk_add_f32 v[66:67], v[66:67], v[104:105] op_sel_hi:[1,0] neg_lo:[0,1] neg_hi:[0,1]
	v_pk_add_f32 v[36:37], v[36:37], v[104:105] op_sel_hi:[1,0] neg_lo:[0,1] neg_hi:[0,1]
	v_pk_add_f32 v[68:69], v[68:69], v[104:105] op_sel_hi:[1,0] neg_lo:[0,1] neg_hi:[0,1]
	v_pk_add_f32 v[38:39], v[38:39], v[104:105] op_sel_hi:[1,0] neg_lo:[0,1] neg_hi:[0,1]
	v_pk_add_f32 v[70:71], v[70:71], v[104:105] op_sel_hi:[1,0] neg_lo:[0,1] neg_hi:[0,1]
	v_pk_add_f32 v[40:41], v[40:41], v[104:105] op_sel_hi:[1,0] neg_lo:[0,1] neg_hi:[0,1]
	v_pk_add_f32 v[72:73], v[72:73], v[104:105] op_sel_hi:[1,0] neg_lo:[0,1] neg_hi:[0,1]
	v_pk_add_f32 v[42:43], v[42:43], v[104:105] op_sel_hi:[1,0] neg_lo:[0,1] neg_hi:[0,1]
	v_pk_add_f32 v[74:75], v[74:75], v[104:105] op_sel_hi:[1,0] neg_lo:[0,1] neg_hi:[0,1]
	v_pk_add_f32 v[44:45], v[44:45], v[104:105] op_sel_hi:[1,0] neg_lo:[0,1] neg_hi:[0,1]
	v_pk_add_f32 v[76:77], v[76:77], v[104:105] op_sel_hi:[1,0] neg_lo:[0,1] neg_hi:[0,1]
	v_pk_add_f32 v[46:47], v[46:47], v[104:105] op_sel_hi:[1,0] neg_lo:[0,1] neg_hi:[0,1]
	v_pk_add_f32 v[78:79], v[78:79], v[104:105] op_sel_hi:[1,0] neg_lo:[0,1] neg_hi:[0,1]
	v_pk_add_f32 v[48:49], v[48:49], v[104:105] op_sel_hi:[1,0] neg_lo:[0,1] neg_hi:[0,1]
	v_cmp_neq_f32_e32 vcc, 1.0, v58
	s_cbranch_vccz .LBB0_1142

.LBB0_1143:
	s_mov_b32 s25, s24
	s_mov_b32 s24, s26
	s_mul_i32 s26, s26, 0x9000
	v_add_u32_e32 v138, s26, v122
	ds_read_b128 v[64:67], v138
	ds_read_b128 v[134:137], v138 offset:4608
	s_mul_i32 s26, s25, 0x9000
	s_waitcnt lgkmcnt(0)
	v_mfma_f32_32x32x16_bf16 v[48:63], v[64:67], v[80:83], v[32:47]
	v_mov_b64_e32 v[78:79], v[46:47]
	v_mov_b64_e32 v[76:77], v[44:45]
	v_mov_b64_e32 v[74:75], v[42:43]
	v_mov_b64_e32 v[72:73], v[40:41]
	v_mov_b64_e32 v[70:71], v[38:39]
	v_mov_b64_e32 v[68:69], v[36:37]
	v_mov_b64_e32 v[66:67], v[34:35]
	v_mov_b64_e32 v[64:65], v[32:33]
	s_waitcnt lgkmcnt(0)
	s_nop 0
	v_mfma_f32_32x32x16_bf16 v[64:79], v[134:137], v[80:83], v[64:79]
	ds_read_b128 v[134:137], v138 offset:32
	s_waitcnt lgkmcnt(0)
	v_mfma_f32_32x32x16_bf16 v[48:63], v[134:137], v[84:87], v[48:63]
	ds_read_b128 v[134:137], v138 offset:4640
	s_waitcnt lgkmcnt(0)
	v_mfma_f32_32x32x16_bf16 v[64:79], v[134:137], v[84:87], v[64:79]
	ds_read_b128 v[134:137], v138 offset:64
	s_waitcnt lgkmcnt(0)
	v_mfma_f32_32x32x16_bf16 v[48:63], v[134:137], v[88:91], v[48:63]
	ds_read_b128 v[134:137], v138 offset:4672
	s_waitcnt lgkmcnt(0)
	v_mfma_f32_32x32x16_bf16 v[64:79], v[134:137], v[88:91], v[64:79]
	ds_read_b128 v[134:137], v138 offset:96
	s_waitcnt lgkmcnt(0)
	v_mfma_f32_32x32x16_bf16 v[48:63], v[134:137], v[92:95], v[48:63]
	ds_read_b128 v[134:137], v138 offset:4704
	v_add_u32_e32 v138, s26, v127
	v_add_u32_e32 v139, 0x4000, v138
	v_add_u32_e32 v138, 0x5000, v138
	s_waitcnt lgkmcnt(0)
	v_mfma_f32_32x32x16_bf16 v[64:79], v[134:137], v[92:95], v[64:79]
	ds_read_b64 v[134:135], v139 offset:1024
	ds_read_b64 v[136:137], v139 offset:1040
	s_waitcnt lgkmcnt(0)
	v_mfma_f32_32x32x16_bf16 v[16:31], v[134:137], v[116:119], v[16:31]
	ds_read_b64 v[134:135], v138 offset:1536
	ds_read_b64 v[136:137], v138 offset:1552
	s_waitcnt lgkmcnt(0)
	v_mfma_f32_32x32x16_bf16 v[0:15], v[134:137], v[116:119], v[0:15]
	ds_read_b64 v[116:117], v139 offset:1056
	ds_read_b64 v[118:119], v139 offset:1072
	s_waitcnt lgkmcnt(0)
	v_mfma_f32_32x32x16_bf16 v[16:31], v[116:119], v[112:115], v[16:31]
	ds_read_b64 v[116:117], v138 offset:1568
	ds_read_b64 v[118:119], v138 offset:1584
	s_waitcnt lgkmcnt(0)
	v_mfma_f32_32x32x16_bf16 v[0:15], v[116:119], v[112:115], v[0:15]
	ds_read_b64 v[112:113], v139 offset:1088
	ds_read_b64 v[114:115], v139 offset:1104
	ds_read_b64 v[116:117], v138 offset:1600
	ds_read_b64 v[118:119], v138 offset:1616
	ds_read_b64 v[134:135], v139 offset:1120
	ds_read_b64 v[136:137], v139 offset:1136
	ds_read_b64 v[140:141], v138 offset:1648
	ds_read_b64 v[138:139], v138 offset:1632
	s_nop 15
	s_nop 7
	s_waitcnt lgkmcnt(6)
	v_mfma_f32_32x32x16_bf16 v[16:31], v[112:115], v[108:111], v[16:31]
	v_max3_f32 v112, v48, v49, v64
	s_nop 0
	v_max3_f32 v112, v112, v65, v50
	s_nop 0
	v_max3_f32 v112, v112, v66, v66
	s_nop 0
	v_max3_f32 v112, v112, v51, v67
	s_waitcnt lgkmcnt(4)
	v_mfma_f32_32x32x16_bf16 v[0:15], v[116:119], v[108:111], v[0:15]
	v_max3_f32 v112, v112, v52, v68
	s_nop 0
	v_max3_f32 v112, v112, v53, v69
	s_nop 0
	v_max3_f32 v112, v112, v54, v70
	s_nop 0
	v_max3_f32 v108, v112, v55, v71
	s_waitcnt lgkmcnt(2)
	v_mfma_f32_32x32x16_bf16 v[16:31], v[134:137], v[104:107], v[16:31]
	v_max3_f32 v108, v108, v56, v72
	s_nop 0
	v_max3_f32 v108, v108, v57, v73
	s_nop 0
	v_max3_f32 v108, v108, v58, v74
	s_nop 0
	v_max3_f32 v108, v108, v59, v75
	s_waitcnt lgkmcnt(0)
	v_mfma_f32_32x32x16_bf16 v[0:15], v[138:141], v[104:107], v[0:15]
	v_max3_f32 v108, v108, v60, v76
	s_nop 0
	v_max3_f32 v108, v108, v61, v77
	s_nop 0
	v_max3_f32 v108, v108, v62, v78
	s_nop 0
	v_max3_f32 v108, v108, v63, v79
	ds_bpermute_b32 v109, v125, v108
	v_max_f32_e32 v108, v108, v108
	s_waitcnt lgkmcnt(0)
	v_max_f32_e32 v109, v109, v109
	v_max_f32_e32 v108, v108, v109
	v_cmp_lt_f32_e32 vcc, 0x41000000, v108
	s_cbranch_vccz .LBB0_1150
	v_max_f32_e32 v32, v108, v108
	v_max_f32_e32 v34, 0, v32
	v_exp_f32_e64 v104, -v34
	v_add_f32_e32 v130, v130, v34
	v_xor_b32_e32 v32, 0x80000000, v130
	v_pk_add_f32 v[48:49], v[48:49], v[34:35] op_sel_hi:[1,0] neg_lo:[0,1] neg_hi:[0,1]
	v_pk_add_f32 v[64:65], v[64:65], v[34:35] op_sel_hi:[1,0] neg_lo:[0,1] neg_hi:[0,1]
	v_pk_add_f32 v[50:51], v[50:51], v[34:35] op_sel_hi:[1,0] neg_lo:[0,1] neg_hi:[0,1]
	v_pk_add_f32 v[66:67], v[66:67], v[34:35] op_sel_hi:[1,0] neg_lo:[0,1] neg_hi:[0,1]
	v_pk_add_f32 v[52:53], v[52:53], v[34:35] op_sel_hi:[1,0] neg_lo:[0,1] neg_hi:[0,1]
	v_pk_add_f32 v[68:69], v[68:69], v[34:35] op_sel_hi:[1,0] neg_lo:[0,1] neg_hi:[0,1]
	v_pk_add_f32 v[54:55], v[54:55], v[34:35] op_sel_hi:[1,0] neg_lo:[0,1] neg_hi:[0,1]
	v_pk_add_f32 v[70:71], v[70:71], v[34:35] op_sel_hi:[1,0] neg_lo:[0,1] neg_hi:[0,1]
	v_pk_add_f32 v[56:57], v[56:57], v[34:35] op_sel_hi:[1,0] neg_lo:[0,1] neg_hi:[0,1]
	v_pk_add_f32 v[72:73], v[72:73], v[34:35] op_sel_hi:[1,0] neg_lo:[0,1] neg_hi:[0,1]
	v_pk_add_f32 v[58:59], v[58:59], v[34:35] op_sel_hi:[1,0] neg_lo:[0,1] neg_hi:[0,1]
	v_pk_add_f32 v[74:75], v[74:75], v[34:35] op_sel_hi:[1,0] neg_lo:[0,1] neg_hi:[0,1]
	v_pk_add_f32 v[60:61], v[60:61], v[34:35] op_sel_hi:[1,0] neg_lo:[0,1] neg_hi:[0,1]
	v_pk_add_f32 v[76:77], v[76:77], v[34:35] op_sel_hi:[1,0] neg_lo:[0,1] neg_hi:[0,1]
	v_pk_add_f32 v[62:63], v[62:63], v[34:35] op_sel_hi:[1,0] neg_lo:[0,1] neg_hi:[0,1]
	v_pk_add_f32 v[78:79], v[78:79], v[34:35] op_sel_hi:[1,0] neg_lo:[0,1] neg_hi:[0,1]
	v_mov_b32_e32 v33, v32
	v_mov_b32_e32 v34, v32
	v_mov_b32_e32 v35, v32
	v_mov_b32_e32 v36, v32
	v_mov_b32_e32 v37, v32
	v_mov_b32_e32 v38, v32
	v_mov_b32_e32 v39, v32
	v_mov_b32_e32 v40, v32
	v_mov_b32_e32 v41, v32
	v_mov_b32_e32 v42, v32
	v_mov_b32_e32 v43, v32
	v_mov_b32_e32 v44, v32
	v_mov_b32_e32 v45, v32
	v_mov_b32_e32 v46, v32
	v_mov_b32_e32 v47, v32
	v_cmp_neq_f32_e32 vcc, 1.0, v104
	s_cbranch_vccz .LBB0_1146

.LBB0_1151:
	ds_read_b64 v[32:33], v126 offset:1024
	ds_read_b64 v[34:35], v126 offset:1040
	ds_read_b64 v[36:37], v126 offset:1056
	ds_read_b64 v[38:39], v126 offset:1072
	s_lshl_b32 s18, s22, 1
	s_add_u32 s18, s59, s18
	s_addc_u32 s19, s60, 0
	s_waitcnt lgkmcnt(0)
	v_mfma_f32_32x32x16_bf16 v[16:31], v[32:35], v[116:119], v[16:31]
	ds_read_b64 v[32:33], v131 offset:1536
	ds_read_b64 v[34:35], v131 offset:1552
	v_lshlrev_b32_e32 v128, 1, v132
	s_waitcnt lgkmcnt(2)
	v_mfma_f32_32x32x16_bf16 v[16:31], v[36:39], v[112:115], v[16:31]
	s_waitcnt lgkmcnt(0)
	v_mfma_f32_32x32x16_bf16 v[0:15], v[32:35], v[116:119], v[0:15]
	ds_read_b64 v[32:33], v131 offset:1568
	ds_read_b64 v[34:35], v131 offset:1584
	s_waitcnt lgkmcnt(0)
	v_mfma_f32_32x32x16_bf16 v[0:15], v[32:35], v[112:115], v[0:15]
	ds_read_b64 v[32:33], v126 offset:1088
	ds_read_b64 v[34:35], v126 offset:1104
	s_waitcnt lgkmcnt(0)
	v_mfma_f32_32x32x16_bf16 v[16:31], v[32:35], v[108:111], v[16:31]
	ds_read_b64 v[32:33], v131 offset:1600
	ds_read_b64 v[34:35], v131 offset:1616
	s_waitcnt lgkmcnt(0)
	v_mfma_f32_32x32x16_bf16 v[0:15], v[32:35], v[108:111], v[0:15]
	ds_read_b64 v[32:33], v126 offset:1120
	ds_read_b64 v[34:35], v126 offset:1136
	s_waitcnt lgkmcnt(0)
	v_mfma_f32_32x32x16_bf16 v[16:31], v[32:35], v[104:107], v[16:31]
	ds_read_b64 v[32:33], v131 offset:1632
	ds_read_b64 v[34:35], v131 offset:1648
	s_waitcnt lgkmcnt(0)
	s_barrier
	v_mfma_f32_32x32x16_bf16 v[0:15], v[32:35], v[104:107], v[0:15]
	ds_bpermute_b32 v32, v125, v48
	s_waitcnt lgkmcnt(0)
	v_add_f32_e32 v32, v48, v32
	v_div_scale_f32 v33, s[20:21], v32, v32, 1.0
	v_rcp_f32_e32 v34, v33
	s_nop 0
	v_fma_f32 v35, -v33, v34, 1.0
	v_fmac_f32_e32 v34, v35, v34
	v_div_scale_f32 v35, vcc, 1.0, v32, 1.0
	v_mul_f32_e32 v36, v35, v34
	v_fma_f32 v37, -v33, v36, v35
	v_fmac_f32_e32 v36, v37, v34
	v_fma_f32 v33, -v33, v36, v35
	v_div_fmas_f32 v33, v33, v34, v36
	v_div_fixup_f32 v32, v33, v32, 1.0
	v_lshl_add_u64 v[34:35], s[18:19], 0, v[128:129]
	v_lshl_add_u64 v[34:35], v[34:35], 0, s[68:69]
	v_lshlrev_b32_e32 v128, 3, v120
	v_pk_mul_f32 v[16:17], v[16:17], v[32:33] op_sel_hi:[1,0]
	v_pk_mul_f32 v[18:19], v[18:19], v[32:33] op_sel_hi:[1,0]
	v_pk_mul_f32 v[0:1], v[0:1], v[32:33] op_sel_hi:[1,0]
	v_pk_mul_f32 v[2:3], v[2:3], v[32:33] op_sel_hi:[1,0]
	v_lshl_add_u64 v[34:35], v[34:35], 0, v[128:129]
	v_cvt_pk_bf16_f32 v16, v16, v17
	v_cvt_pk_bf16_f32 v17, v18, v19
	v_cvt_pk_bf16_f32 v0, v0, v1
	v_cvt_pk_bf16_f32 v1, v2, v3
	global_store_dwordx2 v[34:35], v[16:17], off
	v_pk_mul_f32 v[16:17], v[20:21], v[32:33] op_sel_hi:[1,0]
	v_pk_mul_f32 v[18:19], v[22:23], v[32:33] op_sel_hi:[1,0]
	global_store_dwordx2 v[34:35], v[0:1], off offset:64
	v_pk_mul_f32 v[0:1], v[4:5], v[32:33] op_sel_hi:[1,0]
	v_pk_mul_f32 v[2:3], v[6:7], v[32:33] op_sel_hi:[1,0]
	v_cvt_pk_bf16_f32 v16, v16, v17
	v_cvt_pk_bf16_f32 v17, v18, v19
	v_cvt_pk_bf16_f32 v0, v0, v1
	v_cvt_pk_bf16_f32 v1, v2, v3
	global_store_dwordx2 v[34:35], v[16:17], off offset:16
	v_pk_mul_f32 v[16:17], v[24:25], v[32:33] op_sel_hi:[1,0]
	v_pk_mul_f32 v[18:19], v[26:27], v[32:33] op_sel_hi:[1,0]
	global_store_dwordx2 v[34:35], v[0:1], off offset:80
	v_pk_mul_f32 v[0:1], v[8:9], v[32:33] op_sel_hi:[1,0]
	v_pk_mul_f32 v[2:3], v[10:11], v[32:33] op_sel_hi:[1,0]
	v_cvt_pk_bf16_f32 v16, v16, v17
	v_cvt_pk_bf16_f32 v17, v18, v19
	v_cvt_pk_bf16_f32 v0, v0, v1
	v_cvt_pk_bf16_f32 v1, v2, v3
	global_store_dwordx2 v[34:35], v[16:17], off offset:32
	v_pk_mul_f32 v[16:17], v[28:29], v[32:33] op_sel_hi:[1,0]
	v_pk_mul_f32 v[18:19], v[30:31], v[32:33] op_sel_hi:[1,0]
	global_store_dwordx2 v[34:35], v[0:1], off offset:96
	v_pk_mul_f32 v[0:1], v[12:13], v[32:33] op_sel_hi:[1,0]
	v_pk_mul_f32 v[2:3], v[14:15], v[32:33] op_sel_hi:[1,0]
	v_cvt_pk_bf16_f32 v16, v16, v17
	v_cvt_pk_bf16_f32 v17, v18, v19
	v_cvt_pk_bf16_f32 v0, v0, v1
	v_cvt_pk_bf16_f32 v1, v2, v3
	global_store_dwordx2 v[34:35], v[16:17], off offset:48
	global_store_dwordx2 v[34:35], v[0:1], off offset:112
	s_barrier
	s_branch .LBB0_1168

.LBB0_1153:
	s_mul_i32 s70, s84, 0x9000
	v_add_u32_e32 v208, s70, v154
	s_mov_b32 s71, s65
	s_mul_i32 s68, s71, 0x9000
	s_mov_b32 s65, s84
	v_add_u32_e32 v209, s68, v155
	v_add_u32_e32 v210, 0x4000, v209
	v_add_u32_e32 v211, 0x5000, v209
	ds_read_b128 v[156:159], v208
	ds_read_b128 v[160:163], v208 offset:4608
	ds_read_b128 v[164:167], v208 offset:32
	ds_read_b128 v[168:171], v208 offset:4640
	ds_read_b128 v[172:175], v208 offset:64
	ds_read_b128 v[176:179], v208 offset:4672
	ds_read_b128 v[184:187], v208 offset:96
	ds_read_b128 v[188:191], v208 offset:4704
	s_waitcnt lgkmcnt(6)
	v_mfma_f32_32x32x16_bf16 v[64:79], v[156:159], v[108:111], v[32:47]
	ds_read_b64 v[156:157], v210 offset:1024
	ds_read_b64 v[158:159], v210 offset:1040
	s_mul_i32 s72, s66, 0x9000
	s_add_i32 s73, s72, 0
	v_add3_u32 v218, s73, v150, v151
	v_add3_u32 v219, s73, v152, v153
	v_mfma_f32_32x32x16_bf16 v[80:95], v[160:163], v[108:111], v[32:47]
	ds_read_b64 v[160:161], v211 offset:1536
	ds_read_b64 v[162:163], v211 offset:1552
	s_waitcnt vmcnt(0)
	ds_write_b128 v218, v[116:119]
	ds_write_b128 v219, v[124:127] offset:17408
	s_add_i32 s68, s25, -2
	s_cmp_gt_u32 s68, 33
	s_cbranch_scc1 .Lg4e_nogl
	s_cmp_lt_u32 s68, 30
	s_cselect_b64 s[74:75], -1, 0
	s_and_b64 s[76:77], s[74:75], exec
	s_cselect_b32 s68, 0, 0xffffffe0
	s_add_i32 s68, s68, s25
	s_and_b64 s[76:77], s[74:75], exec
	s_cselect_b32 s73, s21, s27
	s_cselect_b32 s78, s20, s26
	s_lshl_b64 s[76:77], s[68:69], 14
	s_add_u32 s76, s78, s76
	s_addc_u32 s77, s73, s77
	s_and_b64 s[78:79], s[74:75], exec
	s_cselect_b32 s73, s23, s64
	s_cselect_b32 s80, s22, s63
	s_lshl_b32 s68, s68, 6
	s_lshl_b64 s[78:79], s[68:69], 1
	s_add_u32 s78, s80, s78
	s_addc_u32 s79, s73, s79
	v_lshl_add_u64 v[222:223], v[142:143], 1, s[76:77]
	s_and_b64 s[74:75], s[74:75], exec
	v_lshl_add_u64 v[222:223], v[144:145], 1, v[222:223]
	s_cselect_b32 s68, 11, 8
	global_load_dwordx4 v[116:119], v[222:223], off
	v_lshlrev_b64 v[222:223], s68, v[146:147]
	v_lshl_add_u64 v[222:223], v[222:223], 1, s[78:79]
	v_lshl_add_u64 v[222:223], v[222:223], 0, v[128:129]
	global_load_dwordx4 v[124:127], v[222:223], off
.Lg4e_nogl:
	s_waitcnt lgkmcnt(10)
	v_mfma_f32_32x32x16_bf16 v[64:79], v[164:167], v[104:107], v[64:79]
	ds_read_b64 v[164:165], v210 offset:1056
	ds_read_b64 v[166:167], v210 offset:1072
	v_mfma_f32_32x32x16_bf16 v[80:95], v[168:171], v[104:107], v[80:95]
	ds_read_b64 v[168:169], v211 offset:1568
	ds_read_b64 v[170:171], v211 offset:1584
	s_waitcnt lgkmcnt(12)
	v_mfma_f32_32x32x16_bf16 v[64:79], v[172:175], v[100:103], v[64:79]
	ds_read_b64 v[172:173], v210 offset:1088
	ds_read_b64 v[174:175], v210 offset:1104
	v_mfma_f32_32x32x16_bf16 v[80:95], v[176:179], v[100:103], v[80:95]
	ds_read_b64 v[176:177], v211 offset:1600
	ds_read_b64 v[178:179], v211 offset:1616
	s_waitcnt lgkmcnt(14)
	v_mfma_f32_32x32x16_bf16 v[64:79], v[184:187], v[96:99], v[64:79]
	ds_read_b64 v[184:185], v210 offset:1120
	ds_read_b64 v[186:187], v210 offset:1136
	v_mfma_f32_32x32x16_bf16 v[80:95], v[188:191], v[96:99], v[80:95]
	ds_read_b64 v[188:189], v211 offset:1632
	ds_read_b64 v[190:191], v211 offset:1648
	s_waitcnt lgkmcnt(14)
	v_mfma_f32_32x32x16_bf16 v[16:31], v[156:159], v[134:137], v[16:31]
	v_mfma_f32_32x32x16_bf16 v[0:15], v[160:163], v[134:137], v[0:15]
	s_waitcnt lgkmcnt(8)
	v_mfma_f32_32x32x16_bf16 v[16:31], v[164:167], v[130:133], v[16:31]
	v_mfma_f32_32x32x16_bf16 v[0:15], v[168:171], v[130:133], v[0:15]
	s_waitcnt lgkmcnt(4)
	v_mfma_f32_32x32x16_bf16 v[16:31], v[172:175], v[120:123], v[16:31]
	v_mfma_f32_32x32x16_bf16 v[0:15], v[176:179], v[120:123], v[0:15]
	s_waitcnt lgkmcnt(0)
	v_mfma_f32_32x32x16_bf16 v[16:31], v[184:187], v[112:115], v[16:31]
	v_mfma_f32_32x32x16_bf16 v[0:15], v[188:191], v[112:115], v[0:15]
	v_max3_f32 v212, v64, v80, v68
	v_max3_f32 v213, v65, v81, v69
	v_max3_f32 v214, v66, v82, v70
	v_max3_f32 v215, v67, v83, v71
	v_max3_f32 v212, v212, v84, v72
	v_max3_f32 v213, v213, v85, v73
	v_max3_f32 v214, v214, v86, v74
	v_max3_f32 v215, v215, v87, v75
	v_max3_f32 v212, v212, v88, v76
	v_max3_f32 v213, v213, v89, v77
	v_max3_f32 v214, v214, v90, v78
	v_max3_f32 v215, v215, v91, v79
	v_max_f32_e32 v212, v212, v92
	v_max_f32_e32 v213, v213, v93
	v_max_f32_e32 v214, v214, v94
	v_max_f32_e32 v215, v215, v95
	v_max3_f32 v212, v212, v213, v214
	v_max_f32_e32 v212, v212, v215
	v_mov_b32_e32 v216, v212
	v_mov_b32_e32 v217, v212
	s_nop 1
	v_permlane32_swap_b32_e32 v216, v217
	v_max_f32_e32 v212, v216, v217
	v_cmp_lt_f32_e32 vcc, 0x41000000, v212
	s_cbranch_vccz .Lg4e_join
	v_max_f32_e32 v222, 0, v212
	v_add_f32_e32 v149, v149, v222
	v_exp_f32_e64 v216, -v222
	v_xor_b32_e32 v32, 0x80000000, v149
	v_pk_add_f32 v[64:65], v[64:65], v[222:223] op_sel_hi:[1,0] neg_lo:[0,1] neg_hi:[0,1]
	v_pk_add_f32 v[66:67], v[66:67], v[222:223] op_sel_hi:[1,0] neg_lo:[0,1] neg_hi:[0,1]
	v_pk_add_f32 v[68:69], v[68:69], v[222:223] op_sel_hi:[1,0] neg_lo:[0,1] neg_hi:[0,1]
	v_pk_add_f32 v[70:71], v[70:71], v[222:223] op_sel_hi:[1,0] neg_lo:[0,1] neg_hi:[0,1]
	v_pk_add_f32 v[72:73], v[72:73], v[222:223] op_sel_hi:[1,0] neg_lo:[0,1] neg_hi:[0,1]
	v_pk_add_f32 v[74:75], v[74:75], v[222:223] op_sel_hi:[1,0] neg_lo:[0,1] neg_hi:[0,1]
	v_pk_add_f32 v[76:77], v[76:77], v[222:223] op_sel_hi:[1,0] neg_lo:[0,1] neg_hi:[0,1]
	v_pk_add_f32 v[78:79], v[78:79], v[222:223] op_sel_hi:[1,0] neg_lo:[0,1] neg_hi:[0,1]
	v_pk_add_f32 v[80:81], v[80:81], v[222:223] op_sel_hi:[1,0] neg_lo:[0,1] neg_hi:[0,1]
	v_pk_add_f32 v[82:83], v[82:83], v[222:223] op_sel_hi:[1,0] neg_lo:[0,1] neg_hi:[0,1]
	v_pk_add_f32 v[84:85], v[84:85], v[222:223] op_sel_hi:[1,0] neg_lo:[0,1] neg_hi:[0,1]
	v_pk_add_f32 v[86:87], v[86:87], v[222:223] op_sel_hi:[1,0] neg_lo:[0,1] neg_hi:[0,1]
	v_pk_add_f32 v[88:89], v[88:89], v[222:223] op_sel_hi:[1,0] neg_lo:[0,1] neg_hi:[0,1]
	v_pk_add_f32 v[90:91], v[90:91], v[222:223] op_sel_hi:[1,0] neg_lo:[0,1] neg_hi:[0,1]
	v_pk_add_f32 v[92:93], v[92:93], v[222:223] op_sel_hi:[1,0] neg_lo:[0,1] neg_hi:[0,1]
	v_pk_add_f32 v[94:95], v[94:95], v[222:223] op_sel_hi:[1,0] neg_lo:[0,1] neg_hi:[0,1]
	v_mov_b32_e32 v33, v32
	v_mov_b32_e32 v34, v32
	v_mov_b32_e32 v35, v32
	v_mov_b32_e32 v36, v32
	v_mov_b32_e32 v37, v32
	v_mov_b32_e32 v38, v32
	v_mov_b32_e32 v39, v32
	v_mov_b32_e32 v40, v32
	v_mov_b32_e32 v41, v32
	v_mov_b32_e32 v42, v32
	v_mov_b32_e32 v43, v32
	v_mov_b32_e32 v44, v32
	v_mov_b32_e32 v45, v32
	v_mov_b32_e32 v46, v32
	v_mov_b32_e32 v47, v32
	v_mul_f32_e32 v148, v148, v216
	v_pk_mul_f32 v[16:17], v[16:17], v[216:217] op_sel_hi:[1,0]
	v_pk_mul_f32 v[18:19], v[18:19], v[216:217] op_sel_hi:[1,0]
	v_pk_mul_f32 v[20:21], v[20:21], v[216:217] op_sel_hi:[1,0]
	v_pk_mul_f32 v[22:23], v[22:23], v[216:217] op_sel_hi:[1,0]
	v_pk_mul_f32 v[24:25], v[24:25], v[216:217] op_sel_hi:[1,0]
	v_pk_mul_f32 v[26:27], v[26:27], v[216:217] op_sel_hi:[1,0]
	v_pk_mul_f32 v[28:29], v[28:29], v[216:217] op_sel_hi:[1,0]
	v_pk_mul_f32 v[30:31], v[30:31], v[216:217] op_sel_hi:[1,0]
	v_pk_mul_f32 v[0:1], v[0:1], v[216:217] op_sel_hi:[1,0]
	v_pk_mul_f32 v[2:3], v[2:3], v[216:217] op_sel_hi:[1,0]
	v_pk_mul_f32 v[4:5], v[4:5], v[216:217] op_sel_hi:[1,0]
	v_pk_mul_f32 v[6:7], v[6:7], v[216:217] op_sel_hi:[1,0]
	v_pk_mul_f32 v[8:9], v[8:9], v[216:217] op_sel_hi:[1,0]
	v_pk_mul_f32 v[10:11], v[10:11], v[216:217] op_sel_hi:[1,0]
	v_pk_mul_f32 v[12:13], v[12:13], v[216:217] op_sel_hi:[1,0]
	v_pk_mul_f32 v[14:15], v[14:15], v[216:217] op_sel_hi:[1,0]

.Lg4_loop:
	s_mul_i32 s70, s84, 0x9000
	v_add_u32_e32 v208, s70, v154
	s_mov_b32 s71, s65
	s_mul_i32 s68, s71, 0x9000
	s_mov_b32 s65, s84
	v_add_u32_e32 v209, s68, v155
	v_add_u32_e32 v210, 0x4000, v209
	v_add_u32_e32 v211, 0x5000, v209
	ds_read_b128 v[156:159], v208
	ds_read_b128 v[160:163], v208 offset:4608
	ds_read_b128 v[164:167], v208 offset:32
	ds_read_b128 v[168:171], v208 offset:4640
	ds_read_b128 v[172:175], v208 offset:64
	ds_read_b128 v[176:179], v208 offset:4672
	ds_read_b128 v[184:187], v208 offset:96
	ds_read_b128 v[188:191], v208 offset:4704
	s_mul_i32 s72, s66, 0x9000
	s_add_i32 s73, s72, 0
	v_add3_u32 v218, s73, v150, v151
	v_add3_u32 v219, s73, v152, v153
	v_exp_f32_e32 v64, v64
	v_exp_f32_e32 v80, v80
	v_exp_f32_e32 v65, v65
	v_exp_f32_e32 v81, v81
	v_exp_f32_e32 v66, v66
	s_waitcnt lgkmcnt(6)
	v_mfma_f32_32x32x16_bf16 v[48:63], v[156:159], v[108:111], v[32:47]
	ds_read_b64 v[156:157], v210 offset:1024
	ds_read_b64 v[158:159], v210 offset:1040
	v_pk_add_f32 v[214:215], v[64:65], v[80:81]
	v_exp_f32_e32 v82, v82
	v_exp_f32_e32 v67, v67
	v_exp_f32_e32 v83, v83
	v_mfma_f32_32x32x16_bf16 v[192:207], v[160:163], v[108:111], v[32:47]
	ds_read_b64 v[160:161], v211 offset:1536
	ds_read_b64 v[162:163], v211 offset:1552
	s_waitcnt vmcnt(0)
	ds_write_b128 v218, v[116:119]
	ds_write_b128 v219, v[124:127] offset:17408
	s_add_i32 s68, s25, -2
	s_cmp_gt_u32 s68, 33
	s_cbranch_scc1 .Lg4b_nogl
	s_cmp_lt_u32 s68, 30
	s_cselect_b64 s[74:75], -1, 0
	s_and_b64 s[76:77], s[74:75], exec
	s_cselect_b32 s68, 0, 0xffffffe0
	s_add_i32 s68, s68, s25
	s_and_b64 s[76:77], s[74:75], exec
	s_cselect_b32 s73, s21, s27
	s_cselect_b32 s78, s20, s26
	s_lshl_b64 s[76:77], s[68:69], 14
	s_add_u32 s76, s78, s76
	s_addc_u32 s77, s73, s77
	s_and_b64 s[78:79], s[74:75], exec
	s_cselect_b32 s73, s23, s64
	s_cselect_b32 s80, s22, s63
	s_lshl_b32 s68, s68, 6
	s_lshl_b64 s[78:79], s[68:69], 1
	s_add_u32 s78, s80, s78
	s_addc_u32 s79, s73, s79
	v_lshl_add_u64 v[222:223], v[142:143], 1, s[76:77]
	s_and_b64 s[74:75], s[74:75], exec
	v_lshl_add_u64 v[222:223], v[144:145], 1, v[222:223]
	s_cselect_b32 s68, 11, 8
	global_load_dwordx4 v[116:119], v[222:223], off
	v_lshlrev_b64 v[222:223], s68, v[146:147]
	v_lshl_add_u64 v[222:223], v[222:223], 1, s[78:79]
	v_lshl_add_u64 v[222:223], v[222:223], 0, v[128:129]
	global_load_dwordx4 v[124:127], v[222:223], off
.Lg4b_nogl:
	s_waitcnt lgkmcnt(10)
	v_mfma_f32_32x32x16_bf16 v[48:63], v[164:167], v[104:107], v[48:63]
	ds_read_b64 v[164:165], v210 offset:1088
	ds_read_b64 v[166:167], v210 offset:1104
	v_exp_f32_e32 v68, v68
	v_pk_add_f32 v[212:213], v[66:67], v[82:83]
	v_pk_add_f32 v[214:215], v[214:215], v[212:213]
	v_exp_f32_e32 v84, v84
	v_mfma_f32_32x32x16_bf16 v[192:207], v[168:171], v[104:107], v[192:207]
	ds_read_b64 v[168:169], v211 offset:1600
	ds_read_b64 v[170:171], v211 offset:1616
	v_exp_f32_e32 v69, v69
	v_exp_f32_e32 v85, v85
	v_exp_f32_e32 v70, v70
	v_pk_add_f32 v[212:213], v[68:69], v[84:85]
	s_waitcnt lgkmcnt(12)
	v_mfma_f32_32x32x16_bf16 v[48:63], v[172:175], v[100:103], v[48:63]
	ds_read_b64 v[172:173], v210 offset:1056
	ds_read_b64 v[174:175], v210 offset:1072
	v_pk_add_f32 v[214:215], v[214:215], v[212:213]
	v_exp_f32_e32 v86, v86
	v_exp_f32_e32 v71, v71
	v_exp_f32_e32 v87, v87
	v_mfma_f32_32x32x16_bf16 v[192:207], v[176:179], v[100:103], v[192:207]
	ds_read_b64 v[176:177], v211 offset:1568
	ds_read_b64 v[178:179], v211 offset:1584
	v_cvt_pk_bf16_f32 v134, v64, v65
	v_pk_add_f32 v[212:213], v[70:71], v[86:87]
	v_pk_add_f32 v[214:215], v[214:215], v[212:213]
	v_cvt_pk_bf16_f32 v135, v66, v67
	v_cvt_pk_bf16_f32 v136, v68, v69
	v_cvt_pk_bf16_f32 v137, v70, v71
	s_waitcnt lgkmcnt(14)
	v_mfma_f32_32x32x16_bf16 v[48:63], v[184:187], v[96:99], v[48:63]
	ds_read_b64 v[184:185], v210 offset:1120
	ds_read_b64 v[186:187], v210 offset:1136
	v_cvt_pk_bf16_f32 v120, v80, v81
	v_cvt_pk_bf16_f32 v121, v82, v83
	v_cvt_pk_bf16_f32 v122, v84, v85
	v_cvt_pk_bf16_f32 v123, v86, v87
	v_mfma_f32_32x32x16_bf16 v[192:207], v[188:191], v[96:99], v[192:207]
	ds_read_b64 v[188:189], v211 offset:1632
	ds_read_b64 v[190:191], v211 offset:1648
	s_waitcnt lgkmcnt(14)
	v_mfma_f32_32x32x16_bf16 v[16:31], v[156:159], v[134:137], v[16:31]
	v_exp_f32_e32 v72, v72
	v_exp_f32_e32 v88, v88
	v_exp_f32_e32 v73, v73
	v_exp_f32_e32 v89, v89
	v_exp_f32_e32 v74, v74
	v_pk_add_f32 v[212:213], v[72:73], v[88:89]
	v_mfma_f32_32x32x16_bf16 v[0:15], v[160:163], v[134:137], v[0:15]
	v_pk_add_f32 v[214:215], v[214:215], v[212:213]
	v_exp_f32_e32 v90, v90
	v_exp_f32_e32 v75, v75
	v_exp_f32_e32 v91, v91
	v_exp_f32_e32 v76, v76
	v_pk_add_f32 v[212:213], v[74:75], v[90:91]
	s_waitcnt lgkmcnt(8)
	v_mfma_f32_32x32x16_bf16 v[16:31], v[164:167], v[120:123], v[16:31]
	v_pk_add_f32 v[214:215], v[214:215], v[212:213]
	v_exp_f32_e32 v92, v92
	v_exp_f32_e32 v77, v77
	v_exp_f32_e32 v93, v93
	v_exp_f32_e32 v78, v78
	v_mfma_f32_32x32x16_bf16 v[0:15], v[168:171], v[120:123], v[0:15]
	v_pk_add_f32 v[212:213], v[76:77], v[92:93]
	v_pk_add_f32 v[214:215], v[214:215], v[212:213]
	v_exp_f32_e32 v94, v94
	v_exp_f32_e32 v79, v79
	v_exp_f32_e32 v95, v95
	v_cvt_pk_bf16_f32 v130, v72, v73
	v_pk_add_f32 v[212:213], v[78:79], v[94:95]
	v_pk_add_f32 v[214:215], v[214:215], v[212:213]
	v_cvt_pk_bf16_f32 v131, v74, v75
	v_cvt_pk_bf16_f32 v132, v76, v77
	v_cvt_pk_bf16_f32 v133, v78, v79
	s_waitcnt lgkmcnt(4)
	s_nop 0
	v_mfma_f32_32x32x16_bf16 v[16:31], v[172:175], v[130:133], v[16:31]
	v_cvt_pk_bf16_f32 v112, v88, v89
	v_cvt_pk_bf16_f32 v113, v90, v91
	v_cvt_pk_bf16_f32 v114, v92, v93
	v_cvt_pk_bf16_f32 v115, v94, v95
	v_add_f32_e32 v212, v214, v215
	v_add_f32_e32 v148, v148, v212
	v_mfma_f32_32x32x16_bf16 v[0:15], v[176:179], v[130:133], v[0:15]
	v_max3_f32 v212, v48, v192, v52
	v_max3_f32 v213, v49, v193, v53
	v_max3_f32 v214, v50, v194, v54
	v_max3_f32 v215, v51, v195, v55
	v_max3_f32 v212, v212, v196, v56
	v_max3_f32 v213, v213, v197, v57
	v_max3_f32 v214, v214, v198, v58
	v_max3_f32 v215, v215, v199, v59
	v_max3_f32 v212, v212, v200, v60
	s_waitcnt lgkmcnt(0)
	v_mfma_f32_32x32x16_bf16 v[16:31], v[184:187], v[112:115], v[16:31]
	v_max3_f32 v213, v213, v201, v61
	v_max3_f32 v214, v214, v202, v62
	v_max3_f32 v215, v215, v203, v63
	v_max_f32_e32 v212, v212, v204
	v_max_f32_e32 v213, v213, v205
	v_max_f32_e32 v214, v214, v206
	v_max_f32_e32 v215, v215, v207
	v_max3_f32 v212, v212, v213, v214
	v_max_f32_e32 v212, v212, v215
	v_mfma_f32_32x32x16_bf16 v[0:15], v[188:191], v[112:115], v[0:15]
	v_mov_b32_e32 v216, v212
	v_mov_b32_e32 v217, v212
	s_nop 1
	v_permlane32_swap_b32_e32 v216, v217
	v_max_f32_e32 v212, v216, v217
	v_cmp_lt_f32_e32 vcc, 0x41000000, v212
	s_cbranch_vccz .Lg4b_join
	v_max_f32_e32 v222, 0, v212
	v_add_f32_e32 v149, v149, v222
	v_exp_f32_e64 v216, -v222
	v_xor_b32_e32 v32, 0x80000000, v149
	v_pk_add_f32 v[48:49], v[48:49], v[222:223] op_sel_hi:[1,0] neg_lo:[0,1] neg_hi:[0,1]
	v_pk_add_f32 v[50:51], v[50:51], v[222:223] op_sel_hi:[1,0] neg_lo:[0,1] neg_hi:[0,1]
	v_pk_add_f32 v[52:53], v[52:53], v[222:223] op_sel_hi:[1,0] neg_lo:[0,1] neg_hi:[0,1]
	v_pk_add_f32 v[54:55], v[54:55], v[222:223] op_sel_hi:[1,0] neg_lo:[0,1] neg_hi:[0,1]
	v_pk_add_f32 v[56:57], v[56:57], v[222:223] op_sel_hi:[1,0] neg_lo:[0,1] neg_hi:[0,1]
	v_pk_add_f32 v[58:59], v[58:59], v[222:223] op_sel_hi:[1,0] neg_lo:[0,1] neg_hi:[0,1]
	v_pk_add_f32 v[60:61], v[60:61], v[222:223] op_sel_hi:[1,0] neg_lo:[0,1] neg_hi:[0,1]
	v_pk_add_f32 v[62:63], v[62:63], v[222:223] op_sel_hi:[1,0] neg_lo:[0,1] neg_hi:[0,1]
	v_pk_add_f32 v[192:193], v[192:193], v[222:223] op_sel_hi:[1,0] neg_lo:[0,1] neg_hi:[0,1]
	v_pk_add_f32 v[194:195], v[194:195], v[222:223] op_sel_hi:[1,0] neg_lo:[0,1] neg_hi:[0,1]
	v_pk_add_f32 v[196:197], v[196:197], v[222:223] op_sel_hi:[1,0] neg_lo:[0,1] neg_hi:[0,1]
	v_pk_add_f32 v[198:199], v[198:199], v[222:223] op_sel_hi:[1,0] neg_lo:[0,1] neg_hi:[0,1]
	v_pk_add_f32 v[200:201], v[200:201], v[222:223] op_sel_hi:[1,0] neg_lo:[0,1] neg_hi:[0,1]
	v_pk_add_f32 v[202:203], v[202:203], v[222:223] op_sel_hi:[1,0] neg_lo:[0,1] neg_hi:[0,1]
	v_pk_add_f32 v[204:205], v[204:205], v[222:223] op_sel_hi:[1,0] neg_lo:[0,1] neg_hi:[0,1]
	v_pk_add_f32 v[206:207], v[206:207], v[222:223] op_sel_hi:[1,0] neg_lo:[0,1] neg_hi:[0,1]
	v_mov_b32_e32 v33, v32
	v_mov_b32_e32 v34, v32
	v_mov_b32_e32 v35, v32
	v_mov_b32_e32 v36, v32
	v_mov_b32_e32 v37, v32
	v_mov_b32_e32 v38, v32
	v_mov_b32_e32 v39, v32
	v_mov_b32_e32 v40, v32
	v_mov_b32_e32 v41, v32
	v_mov_b32_e32 v42, v32
	v_mov_b32_e32 v43, v32
	v_mov_b32_e32 v44, v32
	v_mov_b32_e32 v45, v32
	v_mov_b32_e32 v46, v32
	v_mov_b32_e32 v47, v32
	v_mul_f32_e32 v148, v148, v216
	v_pk_mul_f32 v[16:17], v[16:17], v[216:217] op_sel_hi:[1,0]
	v_pk_mul_f32 v[18:19], v[18:19], v[216:217] op_sel_hi:[1,0]
	v_pk_mul_f32 v[20:21], v[20:21], v[216:217] op_sel_hi:[1,0]
	v_pk_mul_f32 v[22:23], v[22:23], v[216:217] op_sel_hi:[1,0]
	v_pk_mul_f32 v[24:25], v[24:25], v[216:217] op_sel_hi:[1,0]
	v_pk_mul_f32 v[26:27], v[26:27], v[216:217] op_sel_hi:[1,0]
	v_pk_mul_f32 v[28:29], v[28:29], v[216:217] op_sel_hi:[1,0]
	v_pk_mul_f32 v[30:31], v[30:31], v[216:217] op_sel_hi:[1,0]
	v_pk_mul_f32 v[0:1], v[0:1], v[216:217] op_sel_hi:[1,0]
	v_pk_mul_f32 v[2:3], v[2:3], v[216:217] op_sel_hi:[1,0]
	v_pk_mul_f32 v[4:5], v[4:5], v[216:217] op_sel_hi:[1,0]
	v_pk_mul_f32 v[6:7], v[6:7], v[216:217] op_sel_hi:[1,0]
	v_pk_mul_f32 v[8:9], v[8:9], v[216:217] op_sel_hi:[1,0]
	v_pk_mul_f32 v[10:11], v[10:11], v[216:217] op_sel_hi:[1,0]
	v_pk_mul_f32 v[12:13], v[12:13], v[216:217] op_sel_hi:[1,0]
	v_pk_mul_f32 v[14:15], v[14:15], v[216:217] op_sel_hi:[1,0]
.Lg4b_join:
	s_add_i32 s25, s25, 1
	s_cmp_lg_u32 s25, 37
	s_barrier
	s_cbranch_scc0 .Lg4_exit
	s_mov_b32 s84, s66
	s_mov_b32 s66, s71
	s_mul_i32 s70, s84, 0x9000
	v_add_u32_e32 v208, s70, v154
	s_mov_b32 s71, s65
	s_mul_i32 s68, s71, 0x9000
	s_mov_b32 s65, s84
	v_add_u32_e32 v209, s68, v155
	v_add_u32_e32 v210, 0x4000, v209
	v_add_u32_e32 v211, 0x5000, v209
	ds_read_b128 v[156:159], v208
	ds_read_b128 v[160:163], v208 offset:4608
	ds_read_b128 v[164:167], v208 offset:32
	ds_read_b128 v[168:171], v208 offset:4640
	ds_read_b128 v[172:175], v208 offset:64
	ds_read_b128 v[176:179], v208 offset:4672
	ds_read_b128 v[184:187], v208 offset:96
	ds_read_b128 v[188:191], v208 offset:4704
	s_mul_i32 s72, s66, 0x9000
	s_add_i32 s73, s72, 0
	v_add3_u32 v218, s73, v150, v151
	v_add3_u32 v219, s73, v152, v153
	v_exp_f32_e32 v48, v48
	v_exp_f32_e32 v192, v192
	v_exp_f32_e32 v49, v49
	v_exp_f32_e32 v193, v193
	v_exp_f32_e32 v50, v50
	s_waitcnt lgkmcnt(6)
	v_mfma_f32_32x32x16_bf16 v[64:79], v[156:159], v[108:111], v[32:47]
	ds_read_b64 v[156:157], v210 offset:1024
	ds_read_b64 v[158:159], v210 offset:1040
	v_pk_add_f32 v[214:215], v[48:49], v[192:193]
	v_exp_f32_e32 v194, v194
	v_exp_f32_e32 v51, v51
	v_exp_f32_e32 v195, v195
	v_mfma_f32_32x32x16_bf16 v[80:95], v[160:163], v[108:111], v[32:47]
	ds_read_b64 v[160:161], v211 offset:1536
	ds_read_b64 v[162:163], v211 offset:1552
	s_waitcnt vmcnt(0)
	ds_write_b128 v218, v[116:119]
	ds_write_b128 v219, v[124:127] offset:17408
	s_add_i32 s68, s25, -2
	s_cmp_gt_u32 s68, 33
	s_cbranch_scc1 .Lg4a_nogl
	s_cmp_lt_u32 s68, 30
	s_cselect_b64 s[74:75], -1, 0
	s_and_b64 s[76:77], s[74:75], exec
	s_cselect_b32 s68, 0, 0xffffffe0
	s_add_i32 s68, s68, s25
	s_and_b64 s[76:77], s[74:75], exec
	s_cselect_b32 s73, s21, s27
	s_cselect_b32 s78, s20, s26
	s_lshl_b64 s[76:77], s[68:69], 14
	s_add_u32 s76, s78, s76
	s_addc_u32 s77, s73, s77
	s_and_b64 s[78:79], s[74:75], exec
	s_cselect_b32 s73, s23, s64
	s_cselect_b32 s80, s22, s63
	s_lshl_b32 s68, s68, 6
	s_lshl_b64 s[78:79], s[68:69], 1
	s_add_u32 s78, s80, s78
	s_addc_u32 s79, s73, s79
	v_lshl_add_u64 v[222:223], v[142:143], 1, s[76:77]
	s_and_b64 s[74:75], s[74:75], exec
	v_lshl_add_u64 v[222:223], v[144:145], 1, v[222:223]
	s_cselect_b32 s68, 11, 8
	global_load_dwordx4 v[116:119], v[222:223], off
	v_lshlrev_b64 v[222:223], s68, v[146:147]
	v_lshl_add_u64 v[222:223], v[222:223], 1, s[78:79]
	v_lshl_add_u64 v[222:223], v[222:223], 0, v[128:129]
	global_load_dwordx4 v[124:127], v[222:223], off
.Lg4a_nogl:
	s_waitcnt lgkmcnt(10)
	v_mfma_f32_32x32x16_bf16 v[64:79], v[164:167], v[104:107], v[64:79]
	ds_read_b64 v[164:165], v210 offset:1088
	ds_read_b64 v[166:167], v210 offset:1104
	v_exp_f32_e32 v52, v52
	v_pk_add_f32 v[212:213], v[50:51], v[194:195]
	v_pk_add_f32 v[214:215], v[214:215], v[212:213]
	v_exp_f32_e32 v196, v196
	v_mfma_f32_32x32x16_bf16 v[80:95], v[168:171], v[104:107], v[80:95]
	ds_read_b64 v[168:169], v211 offset:1600
	ds_read_b64 v[170:171], v211 offset:1616
	v_exp_f32_e32 v53, v53
	v_exp_f32_e32 v197, v197
	v_exp_f32_e32 v54, v54
	v_pk_add_f32 v[212:213], v[52:53], v[196:197]
	s_waitcnt lgkmcnt(12)
	v_mfma_f32_32x32x16_bf16 v[64:79], v[172:175], v[100:103], v[64:79]
	ds_read_b64 v[172:173], v210 offset:1056
	ds_read_b64 v[174:175], v210 offset:1072
	v_pk_add_f32 v[214:215], v[214:215], v[212:213]
	v_exp_f32_e32 v198, v198
	v_exp_f32_e32 v55, v55
	v_exp_f32_e32 v199, v199
	v_mfma_f32_32x32x16_bf16 v[80:95], v[176:179], v[100:103], v[80:95]
	ds_read_b64 v[176:177], v211 offset:1568
	ds_read_b64 v[178:179], v211 offset:1584
	v_cvt_pk_bf16_f32 v134, v48, v49
	v_pk_add_f32 v[212:213], v[54:55], v[198:199]
	v_pk_add_f32 v[214:215], v[214:215], v[212:213]
	v_cvt_pk_bf16_f32 v135, v50, v51
	v_cvt_pk_bf16_f32 v136, v52, v53
	v_cvt_pk_bf16_f32 v137, v54, v55
	s_waitcnt lgkmcnt(14)
	v_mfma_f32_32x32x16_bf16 v[64:79], v[184:187], v[96:99], v[64:79]
	ds_read_b64 v[184:185], v210 offset:1120
	ds_read_b64 v[186:187], v210 offset:1136
	v_cvt_pk_bf16_f32 v120, v192, v193
	v_cvt_pk_bf16_f32 v121, v194, v195
	v_cvt_pk_bf16_f32 v122, v196, v197
	v_cvt_pk_bf16_f32 v123, v198, v199
	v_mfma_f32_32x32x16_bf16 v[80:95], v[188:191], v[96:99], v[80:95]
	ds_read_b64 v[188:189], v211 offset:1632
	ds_read_b64 v[190:191], v211 offset:1648
	s_waitcnt lgkmcnt(14)
	v_mfma_f32_32x32x16_bf16 v[16:31], v[156:159], v[134:137], v[16:31]
	v_exp_f32_e32 v56, v56
	v_exp_f32_e32 v200, v200
	v_exp_f32_e32 v57, v57
	v_exp_f32_e32 v201, v201
	v_exp_f32_e32 v58, v58
	v_pk_add_f32 v[212:213], v[56:57], v[200:201]
	v_mfma_f32_32x32x16_bf16 v[0:15], v[160:163], v[134:137], v[0:15]
	v_pk_add_f32 v[214:215], v[214:215], v[212:213]
	v_exp_f32_e32 v202, v202
	v_exp_f32_e32 v59, v59
	v_exp_f32_e32 v203, v203
	v_exp_f32_e32 v60, v60
	v_pk_add_f32 v[212:213], v[58:59], v[202:203]
	s_waitcnt lgkmcnt(8)
	v_mfma_f32_32x32x16_bf16 v[16:31], v[164:167], v[120:123], v[16:31]
	v_pk_add_f32 v[214:215], v[214:215], v[212:213]
	v_exp_f32_e32 v204, v204
	v_exp_f32_e32 v61, v61
	v_exp_f32_e32 v205, v205
	v_exp_f32_e32 v62, v62
	v_mfma_f32_32x32x16_bf16 v[0:15], v[168:171], v[120:123], v[0:15]
	v_pk_add_f32 v[212:213], v[60:61], v[204:205]
	v_pk_add_f32 v[214:215], v[214:215], v[212:213]
	v_exp_f32_e32 v206, v206
	v_exp_f32_e32 v63, v63
	v_exp_f32_e32 v207, v207
	v_cvt_pk_bf16_f32 v130, v56, v57
	v_pk_add_f32 v[212:213], v[62:63], v[206:207]
	v_pk_add_f32 v[214:215], v[214:215], v[212:213]
	v_cvt_pk_bf16_f32 v131, v58, v59
	v_cvt_pk_bf16_f32 v132, v60, v61
	v_cvt_pk_bf16_f32 v133, v62, v63
	s_waitcnt lgkmcnt(4)
	s_nop 0
	v_mfma_f32_32x32x16_bf16 v[16:31], v[172:175], v[130:133], v[16:31]
	v_cvt_pk_bf16_f32 v112, v200, v201
	v_cvt_pk_bf16_f32 v113, v202, v203
	v_cvt_pk_bf16_f32 v114, v204, v205
	v_cvt_pk_bf16_f32 v115, v206, v207
	v_add_f32_e32 v212, v214, v215
	v_add_f32_e32 v148, v148, v212
	v_mfma_f32_32x32x16_bf16 v[0:15], v[176:179], v[130:133], v[0:15]
	v_max3_f32 v212, v64, v80, v68
	v_max3_f32 v213, v65, v81, v69
	v_max3_f32 v214, v66, v82, v70
	v_max3_f32 v215, v67, v83, v71
	v_max3_f32 v212, v212, v84, v72
	v_max3_f32 v213, v213, v85, v73
	v_max3_f32 v214, v214, v86, v74
	v_max3_f32 v215, v215, v87, v75
	v_max3_f32 v212, v212, v88, v76
	s_waitcnt lgkmcnt(0)
	v_mfma_f32_32x32x16_bf16 v[16:31], v[184:187], v[112:115], v[16:31]
	v_max3_f32 v213, v213, v89, v77
	v_max3_f32 v214, v214, v90, v78
	v_max3_f32 v215, v215, v91, v79
	v_max_f32_e32 v212, v212, v92
	v_max_f32_e32 v213, v213, v93
	v_max_f32_e32 v214, v214, v94
	v_max_f32_e32 v215, v215, v95
	v_max3_f32 v212, v212, v213, v214
	v_max_f32_e32 v212, v212, v215
	v_mfma_f32_32x32x16_bf16 v[0:15], v[188:191], v[112:115], v[0:15]
	v_mov_b32_e32 v216, v212
	v_mov_b32_e32 v217, v212
	s_nop 1
	v_permlane32_swap_b32_e32 v216, v217
	v_max_f32_e32 v212, v216, v217
	v_cmp_lt_f32_e32 vcc, 0x41000000, v212
	s_cbranch_vccz .Lg4a_join
	v_max_f32_e32 v222, 0, v212
	v_add_f32_e32 v149, v149, v222
	v_exp_f32_e64 v216, -v222
	v_xor_b32_e32 v32, 0x80000000, v149
	v_pk_add_f32 v[64:65], v[64:65], v[222:223] op_sel_hi:[1,0] neg_lo:[0,1] neg_hi:[0,1]
	v_pk_add_f32 v[66:67], v[66:67], v[222:223] op_sel_hi:[1,0] neg_lo:[0,1] neg_hi:[0,1]
	v_pk_add_f32 v[68:69], v[68:69], v[222:223] op_sel_hi:[1,0] neg_lo:[0,1] neg_hi:[0,1]
	v_pk_add_f32 v[70:71], v[70:71], v[222:223] op_sel_hi:[1,0] neg_lo:[0,1] neg_hi:[0,1]
	v_pk_add_f32 v[72:73], v[72:73], v[222:223] op_sel_hi:[1,0] neg_lo:[0,1] neg_hi:[0,1]
	v_pk_add_f32 v[74:75], v[74:75], v[222:223] op_sel_hi:[1,0] neg_lo:[0,1] neg_hi:[0,1]
	v_pk_add_f32 v[76:77], v[76:77], v[222:223] op_sel_hi:[1,0] neg_lo:[0,1] neg_hi:[0,1]
	v_pk_add_f32 v[78:79], v[78:79], v[222:223] op_sel_hi:[1,0] neg_lo:[0,1] neg_hi:[0,1]
	v_pk_add_f32 v[80:81], v[80:81], v[222:223] op_sel_hi:[1,0] neg_lo:[0,1] neg_hi:[0,1]
	v_pk_add_f32 v[82:83], v[82:83], v[222:223] op_sel_hi:[1,0] neg_lo:[0,1] neg_hi:[0,1]
	v_pk_add_f32 v[84:85], v[84:85], v[222:223] op_sel_hi:[1,0] neg_lo:[0,1] neg_hi:[0,1]
	v_pk_add_f32 v[86:87], v[86:87], v[222:223] op_sel_hi:[1,0] neg_lo:[0,1] neg_hi:[0,1]
	v_pk_add_f32 v[88:89], v[88:89], v[222:223] op_sel_hi:[1,0] neg_lo:[0,1] neg_hi:[0,1]
	v_pk_add_f32 v[90:91], v[90:91], v[222:223] op_sel_hi:[1,0] neg_lo:[0,1] neg_hi:[0,1]
	v_pk_add_f32 v[92:93], v[92:93], v[222:223] op_sel_hi:[1,0] neg_lo:[0,1] neg_hi:[0,1]
	v_pk_add_f32 v[94:95], v[94:95], v[222:223] op_sel_hi:[1,0] neg_lo:[0,1] neg_hi:[0,1]
	v_mov_b32_e32 v33, v32
	v_mov_b32_e32 v34, v32
	v_mov_b32_e32 v35, v32
	v_mov_b32_e32 v36, v32
	v_mov_b32_e32 v37, v32
	v_mov_b32_e32 v38, v32
	v_mov_b32_e32 v39, v32
	v_mov_b32_e32 v40, v32
	v_mov_b32_e32 v41, v32
	v_mov_b32_e32 v42, v32
	v_mov_b32_e32 v43, v32
	v_mov_b32_e32 v44, v32
	v_mov_b32_e32 v45, v32
	v_mov_b32_e32 v46, v32
	v_mov_b32_e32 v47, v32
	v_mul_f32_e32 v148, v148, v216
	v_pk_mul_f32 v[16:17], v[16:17], v[216:217] op_sel_hi:[1,0]
	v_pk_mul_f32 v[18:19], v[18:19], v[216:217] op_sel_hi:[1,0]
	v_pk_mul_f32 v[20:21], v[20:21], v[216:217] op_sel_hi:[1,0]
	v_pk_mul_f32 v[22:23], v[22:23], v[216:217] op_sel_hi:[1,0]
	v_pk_mul_f32 v[24:25], v[24:25], v[216:217] op_sel_hi:[1,0]
	v_pk_mul_f32 v[26:27], v[26:27], v[216:217] op_sel_hi:[1,0]
	v_pk_mul_f32 v[28:29], v[28:29], v[216:217] op_sel_hi:[1,0]
	v_pk_mul_f32 v[30:31], v[30:31], v[216:217] op_sel_hi:[1,0]
	v_pk_mul_f32 v[0:1], v[0:1], v[216:217] op_sel_hi:[1,0]
	v_pk_mul_f32 v[2:3], v[2:3], v[216:217] op_sel_hi:[1,0]
	v_pk_mul_f32 v[4:5], v[4:5], v[216:217] op_sel_hi:[1,0]
	v_pk_mul_f32 v[6:7], v[6:7], v[216:217] op_sel_hi:[1,0]
	v_pk_mul_f32 v[8:9], v[8:9], v[216:217] op_sel_hi:[1,0]
	v_pk_mul_f32 v[10:11], v[10:11], v[216:217] op_sel_hi:[1,0]
	v_pk_mul_f32 v[12:13], v[12:13], v[216:217] op_sel_hi:[1,0]
	v_pk_mul_f32 v[14:15], v[14:15], v[216:217] op_sel_hi:[1,0]

.LBB0_1161:
	v_add_u32_e32 v64, s72, v154
	ds_read_b128 v[66:69], v64
	s_waitcnt lgkmcnt(0)
	v_mfma_f32_32x32x16_bf16 v[32:47], v[66:69], v[108:111], v[48:63]
	ds_read_b128 v[66:69], v64 offset:4608
	s_waitcnt lgkmcnt(0)
	v_mfma_f32_32x32x16_bf16 v[48:63], v[66:69], v[108:111], v[48:63]
	ds_read_b128 v[66:69], v64 offset:32
	s_waitcnt lgkmcnt(0)
	v_mfma_f32_32x32x16_bf16 v[32:47], v[66:69], v[104:107], v[32:47]
	ds_read_b128 v[66:69], v64 offset:4640
	s_waitcnt lgkmcnt(0)
	v_mfma_f32_32x32x16_bf16 v[48:63], v[66:69], v[104:107], v[48:63]
	ds_read_b128 v[66:69], v64 offset:64
	s_waitcnt lgkmcnt(0)
	v_mfma_f32_32x32x16_bf16 v[32:47], v[66:69], v[100:103], v[32:47]
	ds_read_b128 v[66:69], v64 offset:4672
	s_waitcnt lgkmcnt(0)
	v_mfma_f32_32x32x16_bf16 v[48:63], v[66:69], v[100:103], v[48:63]
	ds_read_b128 v[66:69], v64 offset:96
	s_waitcnt lgkmcnt(0)
	v_mfma_f32_32x32x16_bf16 v[32:47], v[66:69], v[96:99], v[32:47]
	ds_read_b128 v[66:69], v64 offset:4704
	v_add_u32_e32 v64, s70, v155
	v_add_u32_e32 v74, 0x4000, v64
	v_add_u32_e32 v64, 0x5000, v64
	s_waitcnt lgkmcnt(0)
	v_mfma_f32_32x32x16_bf16 v[48:63], v[66:69], v[96:99], v[48:63]
	ds_read_b64 v[66:67], v74 offset:1024
	ds_read_b64 v[68:69], v74 offset:1040
	s_waitcnt lgkmcnt(0)
	v_mfma_f32_32x32x16_bf16 v[16:31], v[66:69], v[134:137], v[16:31]
	ds_read_b64 v[66:67], v64 offset:1536
	ds_read_b64 v[68:69], v64 offset:1552
	s_waitcnt lgkmcnt(0)
	v_mfma_f32_32x32x16_bf16 v[0:15], v[66:69], v[134:137], v[0:15]
	ds_read_b64 v[66:67], v74 offset:1056
	ds_read_b64 v[68:69], v74 offset:1072
	s_waitcnt lgkmcnt(0)
	v_mfma_f32_32x32x16_bf16 v[16:31], v[66:69], v[130:133], v[16:31]
	ds_read_b64 v[66:67], v64 offset:1568
	ds_read_b64 v[68:69], v64 offset:1584
	s_waitcnt lgkmcnt(0)
	v_mfma_f32_32x32x16_bf16 v[0:15], v[66:69], v[130:133], v[0:15]
	ds_read_b64 v[66:67], v74 offset:1088
	ds_read_b64 v[68:69], v74 offset:1104
	ds_read_b64 v[70:71], v64 offset:1600
	ds_read_b64 v[72:73], v64 offset:1616
	ds_read_b64 v[76:77], v74 offset:1136
	ds_read_b64 v[74:75], v74 offset:1120
	ds_read_b64 v[78:79], v64 offset:1632
	ds_read_b64 v[80:81], v64 offset:1648
	s_nop 15
	s_nop 7
	s_nop 0
	v_max3_f32 v64, v32, v33, v48
	s_nop 0
	v_max3_f32 v64, v64, v49, v34
	s_nop 0
	v_max3_f32 v64, v64, v50, v50
	s_waitcnt lgkmcnt(6)
	v_mfma_f32_32x32x16_bf16 v[16:31], v[66:69], v[120:123], v[16:31]
	v_max3_f32 v64, v64, v35, v51
	s_nop 0
	v_max3_f32 v64, v64, v36, v52
	s_nop 0
	v_max3_f32 v64, v64, v37, v53
	s_nop 0
	v_max3_f32 v64, v64, v38, v54
	s_waitcnt lgkmcnt(4)
	v_mfma_f32_32x32x16_bf16 v[0:15], v[70:73], v[120:123], v[0:15]
	v_max3_f32 v64, v64, v39, v55
	s_nop 0
	v_max3_f32 v64, v64, v40, v56
	s_nop 0
	v_max3_f32 v64, v64, v41, v57
	s_nop 0
	v_max3_f32 v64, v64, v42, v58
	s_waitcnt lgkmcnt(2)
	v_mfma_f32_32x32x16_bf16 v[16:31], v[74:77], v[112:115], v[16:31]
	v_max3_f32 v64, v64, v43, v59
	s_nop 0
	v_max3_f32 v64, v64, v44, v60
	s_nop 0
	v_max3_f32 v64, v64, v45, v61
	s_nop 0
	v_max3_f32 v64, v64, v46, v62
	s_waitcnt lgkmcnt(0)
	v_mfma_f32_32x32x16_bf16 v[0:15], v[78:81], v[112:115], v[0:15]
	v_max3_f32 v64, v64, v47, v63
	ds_bpermute_b32 v66, v141, v64
	v_max_f32_e32 v64, v64, v64
	s_waitcnt lgkmcnt(0)
	v_max_f32_e32 v66, v66, v66
	v_max_f32_e32 v64, v64, v66
	v_cmp_lt_f32_e32 vcc, 0x41000000, v64
	s_cbranch_vccz .LBB0_1164
	v_max_f32_e32 v64, v64, v64
	v_max_f32_e32 v66, 0, v64
	v_exp_f32_e64 v64, -v66
	v_pk_add_f32 v[32:33], v[32:33], v[66:67] op_sel_hi:[1,0] neg_lo:[0,1] neg_hi:[0,1]
	v_pk_add_f32 v[48:49], v[48:49], v[66:67] op_sel_hi:[1,0] neg_lo:[0,1] neg_hi:[0,1]
	v_pk_add_f32 v[34:35], v[34:35], v[66:67] op_sel_hi:[1,0] neg_lo:[0,1] neg_hi:[0,1]
	v_pk_add_f32 v[50:51], v[50:51], v[66:67] op_sel_hi:[1,0] neg_lo:[0,1] neg_hi:[0,1]
	v_pk_add_f32 v[36:37], v[36:37], v[66:67] op_sel_hi:[1,0] neg_lo:[0,1] neg_hi:[0,1]
	v_pk_add_f32 v[52:53], v[52:53], v[66:67] op_sel_hi:[1,0] neg_lo:[0,1] neg_hi:[0,1]
	v_pk_add_f32 v[38:39], v[38:39], v[66:67] op_sel_hi:[1,0] neg_lo:[0,1] neg_hi:[0,1]
	v_pk_add_f32 v[54:55], v[54:55], v[66:67] op_sel_hi:[1,0] neg_lo:[0,1] neg_hi:[0,1]
	v_pk_add_f32 v[40:41], v[40:41], v[66:67] op_sel_hi:[1,0] neg_lo:[0,1] neg_hi:[0,1]
	v_pk_add_f32 v[56:57], v[56:57], v[66:67] op_sel_hi:[1,0] neg_lo:[0,1] neg_hi:[0,1]
	v_pk_add_f32 v[42:43], v[42:43], v[66:67] op_sel_hi:[1,0] neg_lo:[0,1] neg_hi:[0,1]
	v_pk_add_f32 v[58:59], v[58:59], v[66:67] op_sel_hi:[1,0] neg_lo:[0,1] neg_hi:[0,1]
	v_pk_add_f32 v[44:45], v[44:45], v[66:67] op_sel_hi:[1,0] neg_lo:[0,1] neg_hi:[0,1]
	v_pk_add_f32 v[60:61], v[60:61], v[66:67] op_sel_hi:[1,0] neg_lo:[0,1] neg_hi:[0,1]
	v_pk_add_f32 v[46:47], v[46:47], v[66:67] op_sel_hi:[1,0] neg_lo:[0,1] neg_hi:[0,1]
	v_pk_add_f32 v[62:63], v[62:63], v[66:67] op_sel_hi:[1,0] neg_lo:[0,1] neg_hi:[0,1]
	s_branch .LBB0_1165

.LBB0_1167:
	v_exp_f32_e32 v32, v32
	v_exp_f32_e32 v66, v48
	v_exp_f32_e32 v33, v33
	v_exp_f32_e32 v49, v49
	v_exp_f32_e32 v34, v34
	v_exp_f32_e32 v50, v50
	v_exp_f32_e32 v35, v35
	v_exp_f32_e32 v51, v51
	v_add_f32_e32 v48, v66, v32
	v_exp_f32_e32 v36, v36
	v_exp_f32_e32 v52, v52
	v_add_f32_e32 v48, 0, v48
	v_add_f32_e32 v67, v49, v33
	v_exp_f32_e32 v37, v37
	v_exp_f32_e32 v53, v53
	v_add_f32_e32 v48, v67, v48
	v_add_f32_e32 v67, v50, v34
	v_exp_f32_e32 v38, v38
	v_exp_f32_e32 v54, v54
	v_add_f32_e32 v48, v67, v48
	v_add_f32_e32 v67, v51, v35
	v_exp_f32_e32 v39, v39
	v_exp_f32_e32 v55, v55
	v_add_f32_e32 v48, v67, v48
	v_add_f32_e32 v67, v52, v36
	v_exp_f32_e32 v40, v40
	v_exp_f32_e32 v56, v56
	v_add_f32_e32 v48, v67, v48
	v_add_f32_e32 v67, v53, v37
	v_exp_f32_e32 v41, v41
	v_exp_f32_e32 v57, v57
	v_add_f32_e32 v48, v67, v48
	v_add_f32_e32 v67, v54, v38
	v_exp_f32_e32 v42, v42
	v_exp_f32_e32 v58, v58
	v_add_f32_e32 v48, v67, v48
	v_add_f32_e32 v67, v55, v39
	v_exp_f32_e32 v43, v43
	v_exp_f32_e32 v59, v59
	v_add_f32_e32 v48, v67, v48
	v_add_f32_e32 v67, v56, v40
	v_add_f32_e32 v48, v67, v48
	v_add_f32_e32 v67, v57, v41
	v_add_f32_e32 v48, v67, v48
	v_add_f32_e32 v67, v58, v42
	v_add_f32_e32 v48, v67, v48
	v_add_f32_e32 v67, v59, v43
	v_add_f32_e32 v48, v67, v48
	v_exp_f32_e32 v67, v44
	v_exp_f32_e32 v60, v60
	v_exp_f32_e32 v68, v45
	v_exp_f32_e32 v61, v61
	v_exp_f32_e32 v69, v46
	v_exp_f32_e32 v62, v62
	v_exp_f32_e32 v70, v47
	v_exp_f32_e32 v63, v63
	v_add_f32_e32 v44, v60, v67
	v_add_f32_e32 v44, v44, v48
	v_add_f32_e32 v45, v61, v68
	v_add_f32_e32 v44, v45, v44
	v_add_f32_e32 v45, v62, v69
	v_cvt_pk_bf16_f32 v46, v36, v37
	v_cvt_pk_bf16_f32 v36, v66, v49
	v_add3_u32 v49, v139, v138, 0
	v_add_f32_e32 v44, v45, v44
	v_add_f32_e32 v45, v63, v70
	v_add_u32_e32 v49, 0x16400, v49
	v_add_f32_e32 v48, v45, v44
	v_cvt_pk_bf16_f32 v44, v32, v33
	v_cvt_pk_bf16_f32 v47, v38, v39
	v_cvt_pk_bf16_f32 v37, v50, v51
	v_cvt_pk_bf16_f32 v38, v52, v53
	v_cvt_pk_bf16_f32 v39, v54, v55
	v_cvt_pk_bf16_f32 v32, v56, v57
	s_barrier
	ds_read_b64 v[50:51], v49 offset:0
	ds_read_b64 v[52:53], v49 offset:16
	ds_read_b64 v[54:55], v49 offset:32
	ds_read_b64 v[56:57], v49 offset:48
	v_cvt_pk_bf16_f32 v45, v34, v35
	v_cvt_pk_bf16_f32 v33, v58, v59
	v_add_u32_e32 v58, 0x1000, v49
	s_waitcnt lgkmcnt(0)
	v_mfma_f32_32x32x16_bf16 v[16:31], v[50:53], v[44:47], v[16:31]
	ds_read_b64 v[50:51], v58 offset:512
	ds_read_b64 v[52:53], v58 offset:528
	v_cvt_pk_bf16_f32 v40, v40, v41
	v_cvt_pk_bf16_f32 v41, v42, v43
	v_cvt_pk_bf16_f32 v42, v67, v68
	v_cvt_pk_bf16_f32 v43, v69, v70
	v_cvt_pk_bf16_f32 v34, v60, v61
	v_cvt_pk_bf16_f32 v35, v62, v63
	s_waitcnt lgkmcnt(0)
	v_mfma_f32_32x32x16_bf16 v[0:15], v[50:53], v[44:47], v[0:15]
	ds_read_b64 v[44:45], v58 offset:544
	ds_read_b64 v[46:47], v58 offset:560
	v_fmac_f32_e32 v48, v65, v64
	s_lshl_b64 s[18:19], s[18:19], 1
	s_add_u32 s18, s59, s18
	s_addc_u32 s19, s60, s19
	v_lshlrev_b32_e32 v128, 1, v140
	s_lshl_b32 s68, s24, 1
	v_mfma_f32_32x32x16_bf16 v[16:31], v[54:57], v[40:43], v[16:31]
	v_mov_b32_e32 v139, v129
	s_waitcnt lgkmcnt(0)
	v_mfma_f32_32x32x16_bf16 v[0:15], v[44:47], v[40:43], v[0:15]
	ds_read_b64 v[40:41], v49 offset:64
	ds_read_b64 v[42:43], v49 offset:80
	s_waitcnt lgkmcnt(0)
	v_mfma_f32_32x32x16_bf16 v[16:31], v[40:43], v[36:39], v[16:31]
	ds_read_b64 v[40:41], v58 offset:576
	ds_read_b64 v[42:43], v58 offset:592
	s_waitcnt lgkmcnt(0)
	v_mfma_f32_32x32x16_bf16 v[0:15], v[40:43], v[36:39], v[0:15]
	ds_read_b64 v[36:37], v49 offset:96
	ds_read_b64 v[38:39], v49 offset:112
	s_waitcnt lgkmcnt(0)
	v_mfma_f32_32x32x16_bf16 v[16:31], v[36:39], v[32:35], v[16:31]
	ds_read_b64 v[36:37], v58 offset:608
	ds_read_b64 v[38:39], v58 offset:624
	s_waitcnt lgkmcnt(0)
	s_barrier
	v_mfma_f32_32x32x16_bf16 v[0:15], v[36:39], v[32:35], v[0:15]
	ds_bpermute_b32 v32, v141, v48
	s_waitcnt lgkmcnt(0)
	v_add_f32_e32 v32, v48, v32
	v_div_scale_f32 v33, s[20:21], v32, v32, 1.0
	v_rcp_f32_e32 v34, v33
	s_nop 0
	v_fma_f32 v35, -v33, v34, 1.0
	v_fmac_f32_e32 v34, v35, v34
	v_div_scale_f32 v35, vcc, 1.0, v32, 1.0
	v_mul_f32_e32 v36, v35, v34
	v_fma_f32 v37, -v33, v36, v35
	v_fmac_f32_e32 v36, v37, v34
	v_fma_f32 v33, -v33, v36, v35
	v_div_fmas_f32 v33, v33, v34, v36
	v_div_fixup_f32 v32, v33, v32, 1.0
	v_lshl_add_u64 v[34:35], s[18:19], 0, v[128:129]
	v_lshl_add_u64 v[34:35], v[34:35], 0, s[68:69]
	v_pk_mul_f32 v[16:17], v[16:17], v[32:33] op_sel_hi:[1,0]
	v_pk_mul_f32 v[18:19], v[18:19], v[32:33] op_sel_hi:[1,0]
	v_pk_mul_f32 v[0:1], v[0:1], v[32:33] op_sel_hi:[1,0]
	v_pk_mul_f32 v[2:3], v[2:3], v[32:33] op_sel_hi:[1,0]
	v_lshl_add_u64 v[34:35], v[34:35], 0, v[138:139]
	v_cvt_pk_bf16_f32 v16, v16, v17
	v_cvt_pk_bf16_f32 v17, v18, v19
	v_cvt_pk_bf16_f32 v0, v0, v1
	v_cvt_pk_bf16_f32 v1, v2, v3
	global_store_dwordx2 v[34:35], v[16:17], off
	v_pk_mul_f32 v[16:17], v[20:21], v[32:33] op_sel_hi:[1,0]
	v_pk_mul_f32 v[18:19], v[22:23], v[32:33] op_sel_hi:[1,0]
	global_store_dwordx2 v[34:35], v[0:1], off offset:64
	v_pk_mul_f32 v[0:1], v[4:5], v[32:33] op_sel_hi:[1,0]
	v_pk_mul_f32 v[2:3], v[6:7], v[32:33] op_sel_hi:[1,0]
	v_cvt_pk_bf16_f32 v16, v16, v17
	v_cvt_pk_bf16_f32 v17, v18, v19
	v_cvt_pk_bf16_f32 v0, v0, v1
	v_cvt_pk_bf16_f32 v1, v2, v3
	global_store_dwordx2 v[34:35], v[16:17], off offset:16
	v_pk_mul_f32 v[16:17], v[24:25], v[32:33] op_sel_hi:[1,0]
	v_pk_mul_f32 v[18:19], v[26:27], v[32:33] op_sel_hi:[1,0]
	global_store_dwordx2 v[34:35], v[0:1], off offset:80
	v_pk_mul_f32 v[0:1], v[8:9], v[32:33] op_sel_hi:[1,0]
	v_pk_mul_f32 v[2:3], v[10:11], v[32:33] op_sel_hi:[1,0]
	v_cvt_pk_bf16_f32 v16, v16, v17
	v_cvt_pk_bf16_f32 v17, v18, v19
	v_cvt_pk_bf16_f32 v0, v0, v1
	v_cvt_pk_bf16_f32 v1, v2, v3
	global_store_dwordx2 v[34:35], v[16:17], off offset:32
	v_pk_mul_f32 v[16:17], v[28:29], v[32:33] op_sel_hi:[1,0]
	v_pk_mul_f32 v[18:19], v[30:31], v[32:33] op_sel_hi:[1,0]
	global_store_dwordx2 v[34:35], v[0:1], off offset:96
	v_pk_mul_f32 v[0:1], v[12:13], v[32:33] op_sel_hi:[1,0]
	v_pk_mul_f32 v[2:3], v[14:15], v[32:33] op_sel_hi:[1,0]
	v_cvt_pk_bf16_f32 v16, v16, v17
	v_cvt_pk_bf16_f32 v17, v18, v19
	v_cvt_pk_bf16_f32 v0, v0, v1
	v_cvt_pk_bf16_f32 v1, v2, v3
	global_store_dwordx2 v[34:35], v[16:17], off offset:48
	global_store_dwordx2 v[34:35], v[0:1], off offset:112
	s_barrier

.LBB0_1171:
	s_mul_i32 s68, s85, 0x9000
	v_add_u32_e32 v193, s68, v191
	s_mov_b32 s72, s70
	s_mul_i32 s68, s72, 0x9000
	s_mov_b32 s70, s85
	v_add_u32_e32 v221, s68, v192
	v_add_u32_e32 v222, 0x4000, v221
	v_add_u32_e32 v223, 0x5000, v221
	v_add_u32_e32 v227, 0x6800, v221
	v_add_u32_e32 v232, 0x7800, v221
	ds_read_b128 v[194:197], v193
	ds_read_b128 v[198:201], v193 offset:8704
	ds_read_b128 v[202:205], v193 offset:32
	ds_read_b128 v[206:209], v193 offset:8736
	ds_read_b128 v[210:213], v193 offset:64
	ds_read_b128 v[214:217], v193 offset:8768
	ds_read_b128 v[238:241], v193 offset:96
	s_waitcnt lgkmcnt(5)
	v_mfma_f32_32x32x16_bf16 v[80:95], v[194:197], v[112:115], v[64:79]
	ds_read_b128 v[194:197], v193 offset:8800
	s_mul_i32 s73, s71, 0x9000
	s_add_i32 s73, s73, 0
	v_add_u32_e32 v249, s73, v188
	v_add3_u32 v250, s73, v184, v185
	v_add_u32_e32 v251, v249, v190
	v_add_u32_e32 v249, v249, v189
	v_add3_u32 v218, s73, v186, v187
	v_mfma_f32_32x32x16_bf16 v[96:111], v[198:201], v[112:115], v[64:79]
	ds_read_b64 v[198:199], v222 offset:1024
	ds_read_b64 v[200:201], v222 offset:1040
	s_waitcnt vmcnt(0)
	ds_write_b128 v250, v[130:133]
	ds_write_b128 v218, v[134:137]
	ds_write_b128 v249, v[138:141] offset:17408
	ds_write_b128 v251, v[142:145] offset:17408
	s_waitcnt lgkmcnt(10)
	v_mfma_f32_32x32x16_bf16 v[80:95], v[202:205], v[116:119], v[80:95]
	ds_read_b64 v[202:203], v223 offset:1536
	ds_read_b64 v[204:205], v223 offset:1552
	v_mfma_f32_32x32x16_bf16 v[96:111], v[206:209], v[116:119], v[96:111]
	ds_read_b64 v[206:207], v227 offset:0
	ds_read_b64 v[208:209], v227 offset:16
	s_waitcnt lgkmcnt(12)
	v_mfma_f32_32x32x16_bf16 v[80:95], v[210:213], v[120:123], v[80:95]
	ds_read_b64 v[210:211], v232 offset:512
	ds_read_b64 v[212:213], v232 offset:528
	v_mfma_f32_32x32x16_bf16 v[96:111], v[214:217], v[120:123], v[96:111]
	ds_read_b64 v[214:215], v222 offset:1056
	ds_read_b64 v[216:217], v222 offset:1072
	s_waitcnt lgkmcnt(14)
	v_mfma_f32_32x32x16_bf16 v[80:95], v[238:241], v[124:127], v[80:95]
	ds_read_b64 v[238:239], v223 offset:1568
	ds_read_b64 v[240:241], v223 offset:1584
	v_mfma_f32_32x32x16_bf16 v[96:111], v[194:197], v[124:127], v[96:111]
	ds_read_b64 v[194:195], v227 offset:32
	ds_read_b64 v[196:197], v227 offset:48
	s_waitcnt lgkmcnt(10)
	v_mfma_f32_32x32x16_bf16 v[48:63], v[198:201], v[158:161], v[48:63]
	ds_read_b64 v[198:199], v232 offset:544
	ds_read_b64 v[200:201], v232 offset:560
	v_mfma_f32_32x32x16_bf16 v[32:47], v[202:205], v[158:161], v[32:47]
	ds_read_b64 v[202:203], v222 offset:1088
	ds_read_b64 v[204:205], v222 offset:1104
	s_add_i32 s68, s63, -2
	s_cmp_gt_u32 s68, 33
	s_cbranch_scc1 .Lad_nogl
	s_cmp_lt_u32 s68, 30
	s_cselect_b64 s[74:75], -1, 0
	s_and_b64 s[76:77], s[74:75], exec
	s_cselect_b32 s68, 0, 0xffffffe0
	s_add_i32 s68, s68, s63
	s_and_b64 s[76:77], s[74:75], exec
	s_cselect_b32 s73, s23, s65
	s_cselect_b32 s78, s22, s64
	s_lshl_b64 s[76:77], s[68:69], 16
	s_add_u32 s76, s78, s76
	s_addc_u32 s77, s73, s77
	s_and_b64 s[78:79], s[74:75], exec
	s_cselect_b32 s73, s25, s84
	s_cselect_b32 s80, s24, s66
	s_lshl_b32 s68, s68, 6
	s_lshl_b64 s[78:79], s[68:69], 1
	s_add_u32 s78, s80, s78
	s_addc_u32 s79, s73, s79
	s_and_b64 s[74:75], s[74:75], exec
	s_cselect_b32 s68, 11, 8
	v_lshl_add_u64 v[130:131], v[168:169], 1, s[76:77]
	v_lshl_add_u64 v[132:133], v[172:173], 1, s[76:77]
	v_lshl_add_u64 v[138:139], s[78:79], 0, v[128:129]
	v_lshlrev_b64 v[140:141], s68, v[176:177]
	v_lshlrev_b64 v[142:143], s68, v[178:179]
	v_lshl_add_u64 v[130:131], v[170:171], 1, v[130:131]
	v_lshl_add_u64 v[134:135], v[174:175], 1, v[132:133]
	v_lshl_add_u64 v[140:141], v[140:141], 1, v[138:139]
	v_lshl_add_u64 v[142:143], v[142:143], 1, v[138:139]
	global_load_dwordx4 v[130:133], v[130:131], off
	s_nop 0
	global_load_dwordx4 v[134:137], v[134:135], off
	s_nop 0
	global_load_dwordx4 v[138:141], v[140:141], off
	s_nop 0
	global_load_dwordx4 v[142:145], v[142:143], off
.Lad_nogl:
	s_waitcnt lgkmcnt(10)
	v_mfma_f32_32x32x16_bf16 v[16:31], v[206:209], v[158:161], v[16:31]
	ds_read_b64 v[206:207], v223 offset:1600
	ds_read_b64 v[208:209], v223 offset:1616
	v_mfma_f32_32x32x16_bf16 v[0:15], v[210:213], v[158:161], v[0:15]
	ds_read_b64 v[210:211], v227 offset:64
	ds_read_b64 v[212:213], v227 offset:80
	s_waitcnt lgkmcnt(10)
	v_mfma_f32_32x32x16_bf16 v[48:63], v[214:217], v[154:157], v[48:63]
	ds_read_b64 v[214:215], v232 offset:576
	ds_read_b64 v[216:217], v232 offset:592
	v_max3_f32 v233, v80, v96, v84
	v_max3_f32 v234, v81, v97, v85
	v_max3_f32 v242, v82, v98, v86
	v_max3_f32 v243, v83, v99, v87
	v_max3_f32 v233, v233, v100, v88
	v_max3_f32 v234, v234, v101, v89
	v_mfma_f32_32x32x16_bf16 v[32:47], v[238:241], v[154:157], v[32:47]
	ds_read_b64 v[238:239], v222 offset:1120
	ds_read_b64 v[240:241], v222 offset:1136
	v_max3_f32 v242, v242, v102, v90
	v_max3_f32 v243, v243, v103, v91
	v_max3_f32 v233, v233, v104, v92
	v_max3_f32 v234, v234, v105, v93
	v_max3_f32 v242, v242, v106, v94
	v_max3_f32 v243, v243, v107, v95
	s_waitcnt lgkmcnt(10)
	v_mfma_f32_32x32x16_bf16 v[16:31], v[194:197], v[154:157], v[16:31]
	ds_read_b64 v[194:195], v223 offset:1632
	ds_read_b64 v[196:197], v223 offset:1648
	v_max_f32_e32 v233, v233, v108
	v_max_f32_e32 v234, v234, v109
	v_max_f32_e32 v242, v242, v110
	v_max_f32_e32 v243, v243, v111
	v_max3_f32 v233, v233, v234, v242
	v_max_f32_e32 v233, v233, v243
	v_mfma_f32_32x32x16_bf16 v[0:15], v[198:201], v[154:157], v[0:15]
	ds_read_b64 v[198:199], v227 offset:96
	ds_read_b64 v[200:201], v227 offset:112
	v_mov_b32_e32 v246, v233
	v_mov_b32_e32 v247, v233
	s_nop 1
	v_permlane32_swap_b32_e32 v246, v247
	v_max_f32_e32 v233, v246, v247
	v_cmp_lt_f32_e32 vcc, 0x41000000, v233
	s_cbranch_vccz .Lad_common
	s_waitcnt lgkmcnt(10)
	v_mfma_f32_32x32x16_bf16 v[48:63], v[202:205], v[150:153], v[48:63]
	ds_read_b64 v[202:203], v232 offset:608
	ds_read_b64 v[204:205], v232 offset:624
	v_mfma_f32_32x32x16_bf16 v[32:47], v[206:209], v[150:153], v[32:47]
	s_waitcnt lgkmcnt(8)
	v_mfma_f32_32x32x16_bf16 v[16:31], v[210:213], v[150:153], v[16:31]
	v_mfma_f32_32x32x16_bf16 v[0:15], v[214:217], v[150:153], v[0:15]
	s_waitcnt lgkmcnt(4)
	v_mfma_f32_32x32x16_bf16 v[48:63], v[238:241], v[146:149], v[48:63]
	v_mfma_f32_32x32x16_bf16 v[32:47], v[194:197], v[146:149], v[32:47]
	s_waitcnt lgkmcnt(0)
	v_mfma_f32_32x32x16_bf16 v[16:31], v[198:201], v[146:149], v[16:31]
	v_mfma_f32_32x32x16_bf16 v[0:15], v[202:205], v[146:149], v[0:15]
	s_nop 7
	s_nop 3
	v_max_f32_e32 v64, v233, v233
	v_max_f32_e32 v66, 0, v64
	v_exp_f32_e64 v146, -v66
	v_add_f32_e32 v181, v181, v66
	v_xor_b32_e32 v64, 0x80000000, v181
	v_pk_add_f32 v[80:81], v[80:81], v[66:67] op_sel_hi:[1,0] neg_lo:[0,1] neg_hi:[0,1]
	v_pk_add_f32 v[96:97], v[96:97], v[66:67] op_sel_hi:[1,0] neg_lo:[0,1] neg_hi:[0,1]
	v_pk_add_f32 v[82:83], v[82:83], v[66:67] op_sel_hi:[1,0] neg_lo:[0,1] neg_hi:[0,1]
	v_pk_add_f32 v[98:99], v[98:99], v[66:67] op_sel_hi:[1,0] neg_lo:[0,1] neg_hi:[0,1]
	v_pk_add_f32 v[84:85], v[84:85], v[66:67] op_sel_hi:[1,0] neg_lo:[0,1] neg_hi:[0,1]
	v_pk_add_f32 v[100:101], v[100:101], v[66:67] op_sel_hi:[1,0] neg_lo:[0,1] neg_hi:[0,1]
	v_pk_add_f32 v[86:87], v[86:87], v[66:67] op_sel_hi:[1,0] neg_lo:[0,1] neg_hi:[0,1]
	v_pk_add_f32 v[102:103], v[102:103], v[66:67] op_sel_hi:[1,0] neg_lo:[0,1] neg_hi:[0,1]
	v_pk_add_f32 v[88:89], v[88:89], v[66:67] op_sel_hi:[1,0] neg_lo:[0,1] neg_hi:[0,1]
	v_pk_add_f32 v[104:105], v[104:105], v[66:67] op_sel_hi:[1,0] neg_lo:[0,1] neg_hi:[0,1]
	v_pk_add_f32 v[90:91], v[90:91], v[66:67] op_sel_hi:[1,0] neg_lo:[0,1] neg_hi:[0,1]
	v_pk_add_f32 v[106:107], v[106:107], v[66:67] op_sel_hi:[1,0] neg_lo:[0,1] neg_hi:[0,1]
	v_pk_add_f32 v[92:93], v[92:93], v[66:67] op_sel_hi:[1,0] neg_lo:[0,1] neg_hi:[0,1]
	v_pk_add_f32 v[108:109], v[108:109], v[66:67] op_sel_hi:[1,0] neg_lo:[0,1] neg_hi:[0,1]
	v_pk_add_f32 v[94:95], v[94:95], v[66:67] op_sel_hi:[1,0] neg_lo:[0,1] neg_hi:[0,1]
	v_pk_add_f32 v[110:111], v[110:111], v[66:67] op_sel_hi:[1,0] neg_lo:[0,1] neg_hi:[0,1]
	v_mov_b32_e32 v65, v64
	v_mov_b32_e32 v66, v64
	v_mov_b32_e32 v67, v64
	v_mov_b32_e32 v68, v64
	v_mov_b32_e32 v69, v64
	v_mov_b32_e32 v70, v64
	v_mov_b32_e32 v71, v64
	v_mov_b32_e32 v72, v64
	v_mov_b32_e32 v73, v64
	v_mov_b32_e32 v74, v64
	v_mov_b32_e32 v75, v64
	v_mov_b32_e32 v76, v64
	v_mov_b32_e32 v77, v64
	v_mov_b32_e32 v78, v64
	v_mov_b32_e32 v79, v64
	v_cmp_neq_f32_e32 vcc, 1.0, v146
	s_cbranch_vccz .Lad_rjoin
	v_pk_mul_f32 v[62:63], v[62:63], v[146:147] op_sel_hi:[1,0]
	v_pk_mul_f32 v[60:61], v[60:61], v[146:147] op_sel_hi:[1,0]
	v_pk_mul_f32 v[58:59], v[58:59], v[146:147] op_sel_hi:[1,0]
	v_pk_mul_f32 v[56:57], v[56:57], v[146:147] op_sel_hi:[1,0]
	v_pk_mul_f32 v[54:55], v[54:55], v[146:147] op_sel_hi:[1,0]
	v_pk_mul_f32 v[52:53], v[52:53], v[146:147] op_sel_hi:[1,0]
	v_pk_mul_f32 v[50:51], v[50:51], v[146:147] op_sel_hi:[1,0]
	v_pk_mul_f32 v[48:49], v[48:49], v[146:147] op_sel_hi:[1,0]
	v_pk_mul_f32 v[46:47], v[46:47], v[146:147] op_sel_hi:[1,0]
	v_pk_mul_f32 v[44:45], v[44:45], v[146:147] op_sel_hi:[1,0]
	v_pk_mul_f32 v[42:43], v[42:43], v[146:147] op_sel_hi:[1,0]
	v_pk_mul_f32 v[40:41], v[40:41], v[146:147] op_sel_hi:[1,0]
	v_pk_mul_f32 v[38:39], v[38:39], v[146:147] op_sel_hi:[1,0]
	v_pk_mul_f32 v[36:37], v[36:37], v[146:147] op_sel_hi:[1,0]
	v_pk_mul_f32 v[34:35], v[34:35], v[146:147] op_sel_hi:[1,0]
	v_pk_mul_f32 v[32:33], v[32:33], v[146:147] op_sel_hi:[1,0]
	v_pk_mul_f32 v[30:31], v[30:31], v[146:147] op_sel_hi:[1,0]
	v_pk_mul_f32 v[28:29], v[28:29], v[146:147] op_sel_hi:[1,0]
	v_pk_mul_f32 v[26:27], v[26:27], v[146:147] op_sel_hi:[1,0]
	v_pk_mul_f32 v[24:25], v[24:25], v[146:147] op_sel_hi:[1,0]
	v_pk_mul_f32 v[22:23], v[22:23], v[146:147] op_sel_hi:[1,0]
	v_pk_mul_f32 v[20:21], v[20:21], v[146:147] op_sel_hi:[1,0]
	v_pk_mul_f32 v[18:19], v[18:19], v[146:147] op_sel_hi:[1,0]
	v_pk_mul_f32 v[16:17], v[16:17], v[146:147] op_sel_hi:[1,0]
	v_pk_mul_f32 v[14:15], v[14:15], v[146:147] op_sel_hi:[1,0]
	v_pk_mul_f32 v[12:13], v[12:13], v[146:147] op_sel_hi:[1,0]
	v_pk_mul_f32 v[10:11], v[10:11], v[146:147] op_sel_hi:[1,0]
	v_pk_mul_f32 v[8:9], v[8:9], v[146:147] op_sel_hi:[1,0]
	v_pk_mul_f32 v[6:7], v[6:7], v[146:147] op_sel_hi:[1,0]
	v_pk_mul_f32 v[4:5], v[4:5], v[146:147] op_sel_hi:[1,0]
	v_pk_mul_f32 v[2:3], v[2:3], v[146:147] op_sel_hi:[1,0]
	v_pk_mul_f32 v[0:1], v[0:1], v[146:147] op_sel_hi:[1,0]

.Lad_common:
	s_waitcnt lgkmcnt(10)
	v_mfma_f32_32x32x16_bf16 v[48:63], v[202:205], v[150:153], v[48:63]
	ds_read_b64 v[202:203], v232 offset:608
	ds_read_b64 v[204:205], v232 offset:624
	v_exp_f32_e32 v219, v80
	v_exp_f32_e32 v96, v96
	v_exp_f32_e32 v81, v81
	v_exp_f32_e32 v97, v97
	v_exp_f32_e32 v82, v82
	v_exp_f32_e32 v98, v98
	v_exp_f32_e32 v83, v83
	v_exp_f32_e32 v99, v99
	v_mfma_f32_32x32x16_bf16 v[32:47], v[206:209], v[150:153], v[32:47]
	v_add_f32_e32 v80, v96, v219
	v_exp_f32_e32 v84, v84
	v_exp_f32_e32 v100, v100
	v_add_f32_e32 v80, 0, v80
	v_add_f32_e32 v251, v97, v81
	v_exp_f32_e32 v85, v85
	v_exp_f32_e32 v101, v101
	v_add_f32_e32 v80, v251, v80
	s_waitcnt lgkmcnt(8)
	v_mfma_f32_32x32x16_bf16 v[16:31], v[210:213], v[150:153], v[16:31]
	v_add_f32_e32 v251, v98, v82
	v_exp_f32_e32 v86, v86
	v_exp_f32_e32 v102, v102
	v_add_f32_e32 v80, v251, v80
	v_add_f32_e32 v251, v99, v83
	v_exp_f32_e32 v87, v87
	v_exp_f32_e32 v103, v103
	v_add_f32_e32 v80, v251, v80
	v_mfma_f32_32x32x16_bf16 v[0:15], v[214:217], v[150:153], v[0:15]
	v_add_f32_e32 v251, v100, v84
	v_exp_f32_e32 v88, v88
	v_exp_f32_e32 v104, v104
	v_add_f32_e32 v80, v251, v80
	v_add_f32_e32 v251, v101, v85
	v_exp_f32_e32 v89, v89
	v_exp_f32_e32 v105, v105
	v_add_f32_e32 v80, v251, v80
	s_waitcnt lgkmcnt(4)
	v_mfma_f32_32x32x16_bf16 v[48:63], v[238:241], v[146:149], v[48:63]
	v_add_f32_e32 v251, v102, v86
	v_exp_f32_e32 v90, v90
	v_exp_f32_e32 v106, v106
	v_add_f32_e32 v80, v251, v80
	v_add_f32_e32 v251, v103, v87
	v_exp_f32_e32 v91, v91
	v_exp_f32_e32 v107, v107
	v_add_f32_e32 v80, v251, v80
	v_mfma_f32_32x32x16_bf16 v[32:47], v[194:197], v[146:149], v[32:47]
	v_add_f32_e32 v251, v104, v88
	v_exp_f32_e32 v92, v92
	v_exp_f32_e32 v108, v108
	v_add_f32_e32 v80, v251, v80
	v_add_f32_e32 v251, v105, v89
	v_exp_f32_e32 v93, v93
	v_exp_f32_e32 v109, v109
	v_add_f32_e32 v80, v251, v80
	s_waitcnt lgkmcnt(0)
	v_mfma_f32_32x32x16_bf16 v[16:31], v[198:201], v[146:149], v[16:31]
	v_add_f32_e32 v251, v106, v90
	v_exp_f32_e32 v94, v94
	v_exp_f32_e32 v110, v110
	v_add_f32_e32 v80, v251, v80
	v_add_f32_e32 v251, v107, v91
	v_exp_f32_e32 v95, v95
	v_exp_f32_e32 v111, v111
	v_add_f32_e32 v80, v251, v80
	v_mfma_f32_32x32x16_bf16 v[0:15], v[202:205], v[146:149], v[0:15]
	v_add_f32_e32 v251, v108, v92
	v_add_f32_e32 v80, v251, v80
	v_add_f32_e32 v251, v109, v93
	v_add_f32_e32 v80, v251, v80
	v_add_f32_e32 v251, v110, v94
	v_add_f32_e32 v80, v251, v80
	v_add_f32_e32 v251, v111, v95
	v_add_f32_e32 v80, v251, v80
	v_add_f32_e32 v80, v180, v80
	v_cvt_pk_bf16_f32 v158, v219, v81
	v_cvt_pk_bf16_f32 v159, v82, v83
	v_cvt_pk_bf16_f32 v160, v84, v85
	v_cvt_pk_bf16_f32 v161, v86, v87
	v_cvt_pk_bf16_f32 v150, v96, v97
	v_cvt_pk_bf16_f32 v151, v98, v99
	v_cvt_pk_bf16_f32 v152, v100, v101
	v_cvt_pk_bf16_f32 v153, v102, v103
	v_cvt_pk_bf16_f32 v154, v88, v89
	v_cvt_pk_bf16_f32 v155, v90, v91
	v_cvt_pk_bf16_f32 v156, v92, v93
	v_cvt_pk_bf16_f32 v157, v94, v95
	v_cvt_pk_bf16_f32 v146, v104, v105
	v_cvt_pk_bf16_f32 v147, v106, v107
	v_cvt_pk_bf16_f32 v148, v108, v109
	v_cvt_pk_bf16_f32 v149, v110, v111

.LBB0_1181:
	v_add3_u32 v64, v167, v164, 0
	v_add_u32_e32 v68, 0x16400, v64
	ds_read_b64 v[64:65], v68 offset:0
	ds_read_b64 v[66:67], v68 offset:16
	v_add_u32_e32 v69, 0x1000, v68
	v_add_u32_e32 v72, 0x2000, v68
	v_add_u32_e32 v76, 0x3000, v68
	ds_bpermute_b32 v77, v163, v80
	s_waitcnt lgkmcnt(0)
	v_mfma_f32_32x32x16_bf16 v[48:63], v[64:67], v[158:161], v[48:63]
	ds_read_b64 v[64:65], v69 offset:512
	ds_read_b64 v[66:67], v69 offset:528
	s_waitcnt lgkmcnt(0)
	v_mfma_f32_32x32x16_bf16 v[32:47], v[64:67], v[158:161], v[32:47]
	ds_read_b64 v[64:65], v72 offset:1024
	ds_read_b64 v[66:67], v72 offset:1040
	s_waitcnt lgkmcnt(0)
	v_mfma_f32_32x32x16_bf16 v[16:31], v[64:67], v[158:161], v[16:31]
	ds_read_b64 v[64:65], v76 offset:1536
	ds_read_b64 v[66:67], v76 offset:1552
	s_waitcnt lgkmcnt(0)
	v_mfma_f32_32x32x16_bf16 v[0:15], v[64:67], v[158:161], v[0:15]
	ds_read_b64 v[64:65], v68 offset:32
	ds_read_b64 v[66:67], v68 offset:48
	s_waitcnt lgkmcnt(0)
	v_mfma_f32_32x32x16_bf16 v[48:63], v[64:67], v[154:157], v[48:63]
	ds_read_b64 v[64:65], v69 offset:544
	ds_read_b64 v[66:67], v69 offset:560
	s_waitcnt lgkmcnt(0)
	v_mfma_f32_32x32x16_bf16 v[32:47], v[64:67], v[154:157], v[32:47]
	ds_read_b64 v[64:65], v72 offset:1056
	ds_read_b64 v[66:67], v72 offset:1072
	s_waitcnt lgkmcnt(0)
	v_mfma_f32_32x32x16_bf16 v[16:31], v[64:67], v[154:157], v[16:31]
	ds_read_b64 v[64:65], v76 offset:1568
	ds_read_b64 v[66:67], v76 offset:1584
	s_waitcnt lgkmcnt(0)
	v_mfma_f32_32x32x16_bf16 v[0:15], v[64:67], v[154:157], v[0:15]
	ds_read_b64 v[64:65], v68 offset:64
	ds_read_b64 v[66:67], v68 offset:80
	s_waitcnt lgkmcnt(0)
	v_mfma_f32_32x32x16_bf16 v[48:63], v[64:67], v[150:153], v[48:63]
	ds_read_b64 v[64:65], v69 offset:576
	ds_read_b64 v[66:67], v69 offset:592
	s_waitcnt lgkmcnt(0)
	v_mfma_f32_32x32x16_bf16 v[32:47], v[64:67], v[150:153], v[32:47]
	ds_read_b64 v[64:65], v72 offset:1088
	ds_read_b64 v[66:67], v72 offset:1104
	s_waitcnt lgkmcnt(0)
	v_mfma_f32_32x32x16_bf16 v[16:31], v[64:67], v[150:153], v[16:31]
	ds_read_b64 v[64:65], v76 offset:1600
	ds_read_b64 v[66:67], v76 offset:1616
	s_waitcnt lgkmcnt(0)
	v_mfma_f32_32x32x16_bf16 v[0:15], v[64:67], v[150:153], v[0:15]
	ds_read_b64 v[64:65], v68 offset:96
	ds_read_b64 v[66:67], v68 offset:112
	ds_read_b64 v[70:71], v69 offset:624
	ds_read_b64 v[68:69], v69 offset:608
	ds_read_b64 v[74:75], v72 offset:1136
	ds_read_b64 v[72:73], v72 offset:1120
	s_waitcnt lgkmcnt(4)
	v_mfma_f32_32x32x16_bf16 v[48:63], v[64:67], v[146:149], v[48:63]
	ds_read_b64 v[64:65], v76 offset:1632
	ds_read_b64 v[66:67], v76 offset:1648
	v_add_f32_e32 v76, v80, v77
	v_div_scale_f32 v77, s[22:23], v76, v76, 1.0
	v_rcp_f32_e32 v78, v77
	s_add_i32 s22, s27, 0
	s_cmp_eq_u32 s62, 1
	s_waitcnt lgkmcnt(4)
	v_mfma_f32_32x32x16_bf16 v[32:47], v[68:71], v[146:149], v[32:47]
	v_fma_f32 v68, -v77, v78, 1.0
	v_fmac_f32_e32 v78, v68, v78
	v_div_scale_f32 v68, vcc, 1.0, v76, 1.0
	v_mul_f32_e32 v69, v68, v78
	v_fma_f32 v70, -v77, v69, v68
	v_fmac_f32_e32 v69, v70, v78
	s_waitcnt lgkmcnt(2)
	v_mfma_f32_32x32x16_bf16 v[16:31], v[72:75], v[146:149], v[16:31]
	v_fma_f32 v68, -v77, v69, v68
	v_div_fmas_f32 v68, v68, v78, v69
	v_div_fixup_f32 v70, v68, v76, 1.0
	v_lshl_add_u32 v68, v165, 2, s22
	s_waitcnt lgkmcnt(0)
	s_barrier
	v_mfma_f32_32x32x16_bf16 v[0:15], v[64:67], v[146:149], v[0:15]
	s_cbranch_scc0 .LBB0_1183
	v_mul_f32_e32 v64, v182, v70
	v_mul_f32_e32 v65, v48, v64
	v_mul_f32_e32 v66, v49, v64
	ds_write2st64_b32 v68, v65, v66 offset1:1
	v_mul_f32_e32 v65, v50, v64
	v_mul_f32_e32 v66, v51, v64
	ds_write2st64_b32 v68, v65, v66 offset0:2 offset1:3
	v_mul_f32_e32 v65, v52, v64
	v_mul_f32_e32 v66, v53, v64
	ds_write2st64_b32 v68, v65, v66 offset0:4 offset1:5
	v_mul_f32_e32 v65, v54, v64
	v_mul_f32_e32 v66, v55, v64
	ds_write2st64_b32 v68, v65, v66 offset0:6 offset1:7
	v_mul_f32_e32 v65, v56, v64
	v_mul_f32_e32 v66, v57, v64
	ds_write2st64_b32 v68, v65, v66 offset0:8 offset1:9
	v_mul_f32_e32 v65, v58, v64
	v_mul_f32_e32 v66, v59, v64
	ds_write2st64_b32 v68, v65, v66 offset0:10 offset1:11
	v_mul_f32_e32 v65, v60, v64
	v_mul_f32_e32 v66, v61, v64
	ds_write2st64_b32 v68, v65, v66 offset0:12 offset1:13
	v_mul_f32_e32 v65, v62, v64
	v_mul_f32_e32 v66, v63, v64
	ds_write2st64_b32 v68, v65, v66 offset0:14 offset1:15
	v_mul_f32_e32 v65, v32, v64
	v_mul_f32_e32 v66, v33, v64
	ds_write2st64_b32 v68, v65, v66 offset0:16 offset1:17
	v_mul_f32_e32 v65, v34, v64
	v_mul_f32_e32 v66, v35, v64
	ds_write2st64_b32 v68, v65, v66 offset0:18 offset1:19
	v_mul_f32_e32 v65, v36, v64
	v_mul_f32_e32 v66, v37, v64
	ds_write2st64_b32 v68, v65, v66 offset0:20 offset1:21
	v_mul_f32_e32 v65, v38, v64
	v_mul_f32_e32 v66, v39, v64
	ds_write2st64_b32 v68, v65, v66 offset0:22 offset1:23
	v_mul_f32_e32 v65, v40, v64
	v_mul_f32_e32 v66, v41, v64
	ds_write2st64_b32 v68, v65, v66 offset0:24 offset1:25
	v_mul_f32_e32 v65, v42, v64
	v_mul_f32_e32 v66, v43, v64
	ds_write2st64_b32 v68, v65, v66 offset0:26 offset1:27
	v_mul_f32_e32 v65, v44, v64
	v_mul_f32_e32 v66, v45, v64
	ds_write2st64_b32 v68, v65, v66 offset0:28 offset1:29
	v_mul_f32_e32 v65, v46, v64
	v_mul_f32_e32 v66, v47, v64
	ds_write2st64_b32 v68, v65, v66 offset0:30 offset1:31
	v_mul_f32_e32 v65, v16, v64
	v_mul_f32_e32 v66, v17, v64
	ds_write2st64_b32 v68, v65, v66 offset0:32 offset1:33
	v_mul_f32_e32 v65, v18, v64
	v_mul_f32_e32 v66, v19, v64
	ds_write2st64_b32 v68, v65, v66 offset0:34 offset1:35
	v_mul_f32_e32 v65, v20, v64
	v_mul_f32_e32 v66, v21, v64
	ds_write2st64_b32 v68, v65, v66 offset0:36 offset1:37
	v_mul_f32_e32 v65, v22, v64
	v_mul_f32_e32 v66, v23, v64
	ds_write2st64_b32 v68, v65, v66 offset0:38 offset1:39
	v_mul_f32_e32 v65, v24, v64
	v_mul_f32_e32 v66, v25, v64
	ds_write2st64_b32 v68, v65, v66 offset0:40 offset1:41
	v_mul_f32_e32 v65, v26, v64
	v_mul_f32_e32 v66, v27, v64
	ds_write2st64_b32 v68, v65, v66 offset0:42 offset1:43
	v_mul_f32_e32 v65, v28, v64
	v_mul_f32_e32 v66, v29, v64
	ds_write2st64_b32 v68, v65, v66 offset0:44 offset1:45
	v_mul_f32_e32 v65, v30, v64
	v_mul_f32_e32 v66, v31, v64
	ds_write2st64_b32 v68, v65, v66 offset0:46 offset1:47
	v_mul_f32_e32 v65, v0, v64
	v_mul_f32_e32 v66, v1, v64
	ds_write2st64_b32 v68, v65, v66 offset0:48 offset1:49
	v_mul_f32_e32 v65, v2, v64
	v_mul_f32_e32 v66, v3, v64
	ds_write2st64_b32 v68, v65, v66 offset0:50 offset1:51
	v_mul_f32_e32 v65, v4, v64
	v_mul_f32_e32 v66, v5, v64
	ds_write2st64_b32 v68, v65, v66 offset0:52 offset1:53
	v_mul_f32_e32 v65, v6, v64
	v_mul_f32_e32 v66, v7, v64
	ds_write2st64_b32 v68, v65, v66 offset0:54 offset1:55
	v_mul_f32_e32 v65, v8, v64
	v_mul_f32_e32 v66, v9, v64
	ds_write2st64_b32 v68, v65, v66 offset0:56 offset1:57
	v_mul_f32_e32 v65, v10, v64
	v_mul_f32_e32 v66, v11, v64
	ds_write2st64_b32 v68, v65, v66 offset0:58 offset1:59
	v_mul_f32_e32 v65, v12, v64
	v_mul_f32_e32 v66, v13, v64
	ds_write2st64_b32 v68, v65, v66 offset0:60 offset1:61
	v_mul_f32_e32 v65, v14, v64
	v_mul_f32_e32 v64, v15, v64
	ds_write2st64_b32 v68, v65, v64 offset0:62 offset1:63
